# c15 plus scalar-base addressing for all K-loop LDS-DMA loads (no 64-bit VALU address adds) in the four GEMM phases
# speedup vs baseline: 1.0202x; 1.0025x over previous
.LBB0_318:
	v_add_u32_e32 v146, s58, v176
	v_add_u32_e32 v150, s59, v176
	s_add_u32 s38, s6, s36
	ds_read_b128 v[134:137], v146
	ds_read_b128 v[138:141], v146 offset:1024
	ds_read_b128 v[142:145], v146 offset:2048
	ds_read_b128 v[146:149], v146 offset:3072
	ds_read_b128 v[204:207], v150
	ds_read_b128 v[208:211], v150 offset:1024
	ds_read_b128 v[212:215], v150 offset:2048
	ds_read_b128 v[216:219], v150 offset:3072
	s_addc_u32 s39, s7, s37
	s_mov_b64 s[70:71], s[38:39]
	s_add_u32 s38, s38, 0x100
	s_addc_u32 s39, s39, 0
	s_add_u32 s65, s35, s36
	s_addc_u32 s66, s63, s37
	s_cmpk_eq_i32 s36, 0xf00
	s_cselect_b32 s41, s9, s39
	s_cselect_b32 s40, s27, s38
	s_cselect_b32 s39, s25, s66
	s_cselect_b32 s38, s62, s65
	s_add_i32 m0, s47, 0xc000
	ds_read_b128 v[220:223], v201
	ds_read_b128 v[224:227], v201 offset:1024
	ds_read_b128 v[228:231], v201 offset:2048
	ds_read_b128 v[232:235], v201 offset:3072
	ds_read_b128 v[236:239], v201 offset:4096
	ds_read_b128 v[240:243], v201 offset:5120
	ds_read_b128 v[244:247], v201 offset:6144
	ds_read_b128 v[248:251], v201 offset:7168
	global_load_lds_dwordx4 v170, s[70:71]
	s_add_i32 m0, s47, 0xe000
	s_nop 0
	global_load_lds_dwordx4 v172, s[70:71]
	s_waitcnt vmcnt(8)
	s_waitcnt lgkmcnt(0)
	s_barrier
	s_setprio 1
	s_waitcnt lgkmcnt(0)
	v_mfma_f32_16x16x32_bf16 v[124:127], v[134:137], v[220:223], v[124:127]
	v_mfma_f32_16x16x32_bf16 v[120:123], v[142:145], v[220:223], v[120:123]
	v_mfma_f32_16x16x32_bf16 v[108:111], v[134:137], v[228:231], v[108:111]
	v_mfma_f32_16x16x32_bf16 v[96:99], v[142:145], v[228:231], v[96:99]
	v_mfma_f32_16x16x32_bf16 v[92:95], v[134:137], v[236:239], v[92:95]
	v_mfma_f32_16x16x32_bf16 v[80:83], v[142:145], v[236:239], v[80:83]
	v_mfma_f32_16x16x32_bf16 v[76:79], v[134:137], v[244:247], v[76:79]
	v_mfma_f32_16x16x32_bf16 v[64:67], v[142:145], v[244:247], v[64:67]
	v_mfma_f32_16x16x32_bf16 v[124:127], v[138:141], v[224:227], v[124:127]
	v_mfma_f32_16x16x32_bf16 v[120:123], v[146:149], v[224:227], v[120:123]
	v_mfma_f32_16x16x32_bf16 v[108:111], v[138:141], v[232:235], v[108:111]
	v_mfma_f32_16x16x32_bf16 v[96:99], v[146:149], v[232:235], v[96:99]
	v_mfma_f32_16x16x32_bf16 v[92:95], v[138:141], v[240:243], v[92:95]
	v_mfma_f32_16x16x32_bf16 v[80:83], v[146:149], v[240:243], v[80:83]
	v_mfma_f32_16x16x32_bf16 v[76:79], v[138:141], v[248:251], v[76:79]
	v_mfma_f32_16x16x32_bf16 v[64:67], v[146:149], v[248:251], v[64:67]
	s_setprio 0
	s_setprio 1
	v_mfma_f32_16x16x32_bf16 v[104:107], v[204:207], v[220:223], v[104:107]
	v_mfma_f32_16x16x32_bf16 v[100:103], v[212:215], v[220:223], v[100:103]
	v_mfma_f32_16x16x32_bf16 v[88:91], v[204:207], v[228:231], v[88:91]
	v_mfma_f32_16x16x32_bf16 v[84:87], v[212:215], v[228:231], v[84:87]
	v_mfma_f32_16x16x32_bf16 v[72:75], v[204:207], v[236:239], v[72:75]
	v_mfma_f32_16x16x32_bf16 v[68:71], v[212:215], v[236:239], v[68:71]
	v_mfma_f32_16x16x32_bf16 v[60:63], v[204:207], v[244:247], v[60:63]
	v_mfma_f32_16x16x32_bf16 v[56:59], v[212:215], v[244:247], v[56:59]
	v_mfma_f32_16x16x32_bf16 v[104:107], v[208:211], v[224:227], v[104:107]
	v_mfma_f32_16x16x32_bf16 v[100:103], v[216:219], v[224:227], v[100:103]
	v_mfma_f32_16x16x32_bf16 v[88:91], v[208:211], v[232:235], v[88:91]
	v_mfma_f32_16x16x32_bf16 v[84:87], v[216:219], v[232:235], v[84:87]
	v_mfma_f32_16x16x32_bf16 v[72:75], v[208:211], v[240:243], v[72:75]
	v_mfma_f32_16x16x32_bf16 v[68:71], v[216:219], v[240:243], v[68:71]
	v_mfma_f32_16x16x32_bf16 v[60:63], v[208:211], v[248:251], v[60:63]
	v_mfma_f32_16x16x32_bf16 v[56:59], v[216:219], v[248:251], v[56:59]
	s_setprio 0
	s_barrier
	s_add_i32 s65, s58, s46
	s_add_u32 s74, s38, 0x80
	s_addc_u32 s75, s39, 0
	s_mov_b32 m0, s65
	ds_read_b128 v[220:223], v201 offset:16384
	ds_read_b128 v[224:227], v201 offset:17408
	ds_read_b128 v[228:231], v201 offset:18432
	ds_read_b128 v[232:235], v201 offset:19456
	ds_read_b128 v[236:239], v201 offset:20480
	ds_read_b128 v[240:243], v201 offset:21504
	ds_read_b128 v[244:247], v201 offset:22528
	ds_read_b128 v[248:251], v201 offset:23552
	global_load_lds_dwordx4 v154, s[38:39]
	s_add_i32 m0, s65, 0x2000
	s_add_u32 s66, s38, 0x80000
	s_addc_u32 s67, s39, 0
	s_add_i32 s65, s59, s46
	global_load_lds_dwordx4 v158, s[38:39]
	s_mov_b32 m0, s65
	s_nop 0
	global_load_lds_dwordx4 v154, s[66:67]
	s_add_i32 m0, s65, 0x2000
	s_nop 0
	global_load_lds_dwordx4 v158, s[66:67]
	s_add_u32 s78, s40, 0x80
	s_addc_u32 s79, s41, 0
	s_mov_b32 m0, s47
	s_nop 0
	global_load_lds_dwordx4 v152, s[40:41]
	s_mov_b32 m0, s48
	s_nop 0
	global_load_lds_dwordx4 v156, s[40:41]
	s_waitcnt vmcnt(8)
	s_waitcnt lgkmcnt(0)
	s_barrier
	s_setprio 1
	s_waitcnt lgkmcnt(0)
	v_mfma_f32_16x16x32_bf16 v[52:55], v[134:137], v[220:223], v[52:55]
	v_mfma_f32_16x16x32_bf16 v[48:51], v[142:145], v[220:223], v[48:51]
	v_mfma_f32_16x16x32_bf16 v[44:47], v[134:137], v[228:231], v[44:47]
	v_mfma_f32_16x16x32_bf16 v[32:35], v[142:145], v[228:231], v[32:35]
	v_mfma_f32_16x16x32_bf16 v[28:31], v[134:137], v[236:239], v[28:31]
	v_mfma_f32_16x16x32_bf16 v[16:19], v[142:145], v[236:239], v[16:19]
	v_mfma_f32_16x16x32_bf16 v[116:119], v[134:137], v[244:247], v[116:119]
	v_mfma_f32_16x16x32_bf16 v[112:115], v[142:145], v[244:247], v[112:115]
	v_mfma_f32_16x16x32_bf16 v[52:55], v[138:141], v[224:227], v[52:55]
	v_mfma_f32_16x16x32_bf16 v[48:51], v[146:149], v[224:227], v[48:51]
	v_mfma_f32_16x16x32_bf16 v[44:47], v[138:141], v[232:235], v[44:47]
	v_mfma_f32_16x16x32_bf16 v[32:35], v[146:149], v[232:235], v[32:35]
	v_mfma_f32_16x16x32_bf16 v[28:31], v[138:141], v[240:243], v[28:31]
	v_mfma_f32_16x16x32_bf16 v[16:19], v[146:149], v[240:243], v[16:19]
	v_mfma_f32_16x16x32_bf16 v[116:119], v[138:141], v[248:251], v[116:119]
	v_mfma_f32_16x16x32_bf16 v[112:115], v[146:149], v[248:251], v[112:115]
	s_setprio 0
	s_setprio 1
	v_mfma_f32_16x16x32_bf16 v[40:43], v[204:207], v[220:223], v[40:43]
	v_mfma_f32_16x16x32_bf16 v[36:39], v[212:215], v[220:223], v[36:39]
	v_mfma_f32_16x16x32_bf16 v[24:27], v[204:207], v[228:231], v[24:27]
	v_mfma_f32_16x16x32_bf16 v[20:23], v[212:215], v[228:231], v[20:23]
	v_mfma_f32_16x16x32_bf16 v[12:15], v[204:207], v[236:239], v[12:15]
	v_mfma_f32_16x16x32_bf16 v[8:11], v[212:215], v[236:239], v[8:11]
	v_mfma_f32_16x16x32_bf16 v[4:7], v[204:207], v[244:247], v[4:7]
	v_mfma_f32_16x16x32_bf16 v[0:3], v[212:215], v[244:247], v[0:3]
	v_mfma_f32_16x16x32_bf16 v[40:43], v[208:211], v[224:227], v[40:43]
	v_mfma_f32_16x16x32_bf16 v[36:39], v[216:219], v[224:227], v[36:39]
	v_mfma_f32_16x16x32_bf16 v[24:27], v[208:211], v[232:235], v[24:27]
	v_mfma_f32_16x16x32_bf16 v[20:23], v[216:219], v[232:235], v[20:23]
	v_mfma_f32_16x16x32_bf16 v[12:15], v[208:211], v[240:243], v[12:15]
	v_mfma_f32_16x16x32_bf16 v[8:11], v[216:219], v[240:243], v[8:11]
	v_mfma_f32_16x16x32_bf16 v[4:7], v[208:211], v[248:251], v[4:7]
	v_mfma_f32_16x16x32_bf16 v[0:3], v[216:219], v[248:251], v[0:3]
	s_setprio 0
	s_barrier
	s_add_i32 s65, 0, 0x18000
	s_add_i32 s66, 0, 0x1c000
	v_add_u32_e32 v146, s65, v176
	v_add_u32_e32 v160, s66, v176
	ds_read_b128 v[134:137], v146
	ds_read_b128 v[138:141], v146 offset:1024
	ds_read_b128 v[142:145], v146 offset:2048
	ds_read_b128 v[146:149], v146 offset:3072
	ds_read_b128 v[204:207], v160
	ds_read_b128 v[208:211], v160 offset:1024
	ds_read_b128 v[212:215], v160 offset:2048
	ds_read_b128 v[216:219], v160 offset:3072
	s_add_u32 s40, s40, 0x80000
	s_addc_u32 s41, s41, 0
	s_mov_b32 m0, s49
	ds_read_b128 v[220:223], v201 offset:32768
	ds_read_b128 v[224:227], v201 offset:33792
	ds_read_b128 v[228:231], v201 offset:34816
	ds_read_b128 v[232:235], v201 offset:35840
	ds_read_b128 v[236:239], v201 offset:36864
	ds_read_b128 v[240:243], v201 offset:37888
	ds_read_b128 v[244:247], v201 offset:38912
	ds_read_b128 v[248:251], v201 offset:39936
	global_load_lds_dwordx4 v152, s[40:41]
	s_mov_b32 m0, s50
	s_nop 0
	global_load_lds_dwordx4 v156, s[40:41]
	s_waitcnt vmcnt(8)
	s_waitcnt lgkmcnt(0)
	s_barrier
	s_setprio 1
	s_waitcnt lgkmcnt(0)
	v_mfma_f32_16x16x32_bf16 v[124:127], v[134:137], v[220:223], v[124:127]
	v_mfma_f32_16x16x32_bf16 v[120:123], v[142:145], v[220:223], v[120:123]
	v_mfma_f32_16x16x32_bf16 v[108:111], v[134:137], v[228:231], v[108:111]
	v_mfma_f32_16x16x32_bf16 v[96:99], v[142:145], v[228:231], v[96:99]
	v_mfma_f32_16x16x32_bf16 v[92:95], v[134:137], v[236:239], v[92:95]
	v_mfma_f32_16x16x32_bf16 v[80:83], v[142:145], v[236:239], v[80:83]
	v_mfma_f32_16x16x32_bf16 v[76:79], v[134:137], v[244:247], v[76:79]
	v_mfma_f32_16x16x32_bf16 v[64:67], v[142:145], v[244:247], v[64:67]
	v_mfma_f32_16x16x32_bf16 v[124:127], v[138:141], v[224:227], v[124:127]
	v_mfma_f32_16x16x32_bf16 v[120:123], v[146:149], v[224:227], v[120:123]
	v_mfma_f32_16x16x32_bf16 v[108:111], v[138:141], v[232:235], v[108:111]
	v_mfma_f32_16x16x32_bf16 v[96:99], v[146:149], v[232:235], v[96:99]
	v_mfma_f32_16x16x32_bf16 v[92:95], v[138:141], v[240:243], v[92:95]
	v_mfma_f32_16x16x32_bf16 v[80:83], v[146:149], v[240:243], v[80:83]
	v_mfma_f32_16x16x32_bf16 v[76:79], v[138:141], v[248:251], v[76:79]
	v_mfma_f32_16x16x32_bf16 v[64:67], v[146:149], v[248:251], v[64:67]
	s_setprio 0
	s_setprio 1
	v_mfma_f32_16x16x32_bf16 v[104:107], v[204:207], v[220:223], v[104:107]
	v_mfma_f32_16x16x32_bf16 v[100:103], v[212:215], v[220:223], v[100:103]
	v_mfma_f32_16x16x32_bf16 v[88:91], v[204:207], v[228:231], v[88:91]
	v_mfma_f32_16x16x32_bf16 v[84:87], v[212:215], v[228:231], v[84:87]
	v_mfma_f32_16x16x32_bf16 v[72:75], v[204:207], v[236:239], v[72:75]
	v_mfma_f32_16x16x32_bf16 v[68:71], v[212:215], v[236:239], v[68:71]
	v_mfma_f32_16x16x32_bf16 v[60:63], v[204:207], v[244:247], v[60:63]
	v_mfma_f32_16x16x32_bf16 v[56:59], v[212:215], v[244:247], v[56:59]
	v_mfma_f32_16x16x32_bf16 v[104:107], v[208:211], v[224:227], v[104:107]
	v_mfma_f32_16x16x32_bf16 v[100:103], v[216:219], v[224:227], v[100:103]
	v_mfma_f32_16x16x32_bf16 v[88:91], v[208:211], v[232:235], v[88:91]
	v_mfma_f32_16x16x32_bf16 v[84:87], v[216:219], v[232:235], v[84:87]
	v_mfma_f32_16x16x32_bf16 v[72:75], v[208:211], v[240:243], v[72:75]
	v_mfma_f32_16x16x32_bf16 v[68:71], v[216:219], v[240:243], v[68:71]
	v_mfma_f32_16x16x32_bf16 v[60:63], v[208:211], v[248:251], v[60:63]
	v_mfma_f32_16x16x32_bf16 v[56:59], v[216:219], v[248:251], v[56:59]
	s_setprio 0
	s_barrier
	s_add_i32 s40, s65, s46
	s_mov_b32 m0, s40
	ds_read_b128 v[220:223], v201 offset:49152
	ds_read_b128 v[224:227], v201 offset:50176
	ds_read_b128 v[228:231], v201 offset:51200
	ds_read_b128 v[232:235], v201 offset:52224
	ds_read_b128 v[236:239], v201 offset:53248
	ds_read_b128 v[240:243], v201 offset:54272
	ds_read_b128 v[244:247], v201 offset:55296
	ds_read_b128 v[248:251], v201 offset:56320
	global_load_lds_dwordx4 v154, s[74:75]
	s_add_i32 m0, s40, 0x2000
	s_add_u32 s38, s38, 0x80080
	s_addc_u32 s39, s39, 0
	s_add_i32 s40, s66, s46
	global_load_lds_dwordx4 v158, s[74:75]
	s_mov_b32 m0, s40
	s_nop 0
	global_load_lds_dwordx4 v154, s[38:39]
	s_add_i32 m0, s40, 0x2000
	s_nop 0
	global_load_lds_dwordx4 v158, s[38:39]
	s_mov_b32 m0, s53
	s_nop 0
	global_load_lds_dwordx4 v152, s[78:79]
	s_mov_b32 m0, s54
	s_nop 0
	global_load_lds_dwordx4 v156, s[78:79]
	s_waitcnt vmcnt(8)
	s_waitcnt lgkmcnt(0)
	s_barrier
	s_setprio 1
	s_waitcnt lgkmcnt(0)
	v_mfma_f32_16x16x32_bf16 v[52:55], v[134:137], v[220:223], v[52:55]
	v_mfma_f32_16x16x32_bf16 v[48:51], v[142:145], v[220:223], v[48:51]
	v_mfma_f32_16x16x32_bf16 v[44:47], v[134:137], v[228:231], v[44:47]
	v_mfma_f32_16x16x32_bf16 v[32:35], v[142:145], v[228:231], v[32:35]
	v_mfma_f32_16x16x32_bf16 v[28:31], v[134:137], v[236:239], v[28:31]
	v_mfma_f32_16x16x32_bf16 v[16:19], v[142:145], v[236:239], v[16:19]
	v_mfma_f32_16x16x32_bf16 v[116:119], v[134:137], v[244:247], v[116:119]
	v_mfma_f32_16x16x32_bf16 v[112:115], v[142:145], v[244:247], v[112:115]
	v_mfma_f32_16x16x32_bf16 v[52:55], v[138:141], v[224:227], v[52:55]
	v_mfma_f32_16x16x32_bf16 v[48:51], v[146:149], v[224:227], v[48:51]
	v_mfma_f32_16x16x32_bf16 v[44:47], v[138:141], v[232:235], v[44:47]
	v_mfma_f32_16x16x32_bf16 v[32:35], v[146:149], v[232:235], v[32:35]
	v_mfma_f32_16x16x32_bf16 v[28:31], v[138:141], v[240:243], v[28:31]
	v_mfma_f32_16x16x32_bf16 v[16:19], v[146:149], v[240:243], v[16:19]
	v_mfma_f32_16x16x32_bf16 v[116:119], v[138:141], v[248:251], v[116:119]
	v_mfma_f32_16x16x32_bf16 v[112:115], v[146:149], v[248:251], v[112:115]
	s_setprio 0
	s_setprio 1
	v_mfma_f32_16x16x32_bf16 v[40:43], v[204:207], v[220:223], v[40:43]
	v_mfma_f32_16x16x32_bf16 v[36:39], v[212:215], v[220:223], v[36:39]
	v_mfma_f32_16x16x32_bf16 v[24:27], v[204:207], v[228:231], v[24:27]
	v_mfma_f32_16x16x32_bf16 v[20:23], v[212:215], v[228:231], v[20:23]
	v_mfma_f32_16x16x32_bf16 v[12:15], v[204:207], v[236:239], v[12:15]
	v_mfma_f32_16x16x32_bf16 v[8:11], v[212:215], v[236:239], v[8:11]
	v_mfma_f32_16x16x32_bf16 v[4:7], v[204:207], v[244:247], v[4:7]
	v_mfma_f32_16x16x32_bf16 v[0:3], v[212:215], v[244:247], v[0:3]
	v_mfma_f32_16x16x32_bf16 v[40:43], v[208:211], v[224:227], v[40:43]
	v_mfma_f32_16x16x32_bf16 v[36:39], v[216:219], v[224:227], v[36:39]
	v_mfma_f32_16x16x32_bf16 v[24:27], v[208:211], v[232:235], v[24:27]
	v_mfma_f32_16x16x32_bf16 v[20:23], v[216:219], v[232:235], v[20:23]
	v_mfma_f32_16x16x32_bf16 v[12:15], v[208:211], v[240:243], v[12:15]
	v_mfma_f32_16x16x32_bf16 v[8:11], v[216:219], v[240:243], v[8:11]
	v_mfma_f32_16x16x32_bf16 v[4:7], v[208:211], v[248:251], v[4:7]
	v_mfma_f32_16x16x32_bf16 v[0:3], v[216:219], v[248:251], v[0:3]
	s_setprio 0
	s_barrier
	s_add_i32 s64, s64, 2
	s_add_u32 s36, s36, 0x100
	s_addc_u32 s37, s37, 0
	s_cmp_gt_u32 s64, 29
	s_cbranch_scc1 .LBB0_321

.Lpeel_p1:
	v_add_u32_e32 v146, s58, v176
	v_add_u32_e32 v150, s59, v176
	s_add_u32 s38, s6, s36
	ds_read_b128 v[134:137], v146
	ds_read_b128 v[138:141], v146 offset:1024
	ds_read_b128 v[142:145], v146 offset:2048
	ds_read_b128 v[146:149], v146 offset:3072
	ds_read_b128 v[204:207], v150
	ds_read_b128 v[208:211], v150 offset:1024
	ds_read_b128 v[212:215], v150 offset:2048
	ds_read_b128 v[216:219], v150 offset:3072
	s_addc_u32 s39, s7, s37
	s_mov_b64 s[70:71], s[38:39]
	s_add_u32 s38, s38, 0x100
	s_addc_u32 s39, s39, 0
	s_add_u32 s65, s35, s36
	s_addc_u32 s66, s63, s37
	s_cmpk_eq_i32 s36, 0xf00
	s_cselect_b32 s41, s9, s39
	s_cselect_b32 s40, s27, s38
	s_cselect_b32 s39, s25, s66
	s_cselect_b32 s38, s62, s65
	s_add_i32 m0, s47, 0xc000
	ds_read_b128 v[220:223], v201
	ds_read_b128 v[224:227], v201 offset:1024
	ds_read_b128 v[228:231], v201 offset:2048
	ds_read_b128 v[232:235], v201 offset:3072
	ds_read_b128 v[236:239], v201 offset:4096
	ds_read_b128 v[240:243], v201 offset:5120
	ds_read_b128 v[244:247], v201 offset:6144
	ds_read_b128 v[248:251], v201 offset:7168
	global_load_lds_dwordx4 v170, s[70:71]
	s_add_i32 m0, s47, 0xe000
	s_nop 0
	global_load_lds_dwordx4 v172, s[70:71]
	s_waitcnt vmcnt(8)
	s_waitcnt lgkmcnt(0)
	s_barrier
	s_setprio 1
	s_waitcnt lgkmcnt(0)
	v_mfma_f32_16x16x32_bf16 v[124:127], v[134:137], v[220:223], 0
	v_mfma_f32_16x16x32_bf16 v[120:123], v[142:145], v[220:223], 0
	v_mfma_f32_16x16x32_bf16 v[108:111], v[134:137], v[228:231], 0
	v_mfma_f32_16x16x32_bf16 v[96:99], v[142:145], v[228:231], 0
	v_mfma_f32_16x16x32_bf16 v[92:95], v[134:137], v[236:239], 0
	v_mfma_f32_16x16x32_bf16 v[80:83], v[142:145], v[236:239], 0
	v_mfma_f32_16x16x32_bf16 v[76:79], v[134:137], v[244:247], 0
	v_mfma_f32_16x16x32_bf16 v[64:67], v[142:145], v[244:247], 0
	v_mfma_f32_16x16x32_bf16 v[124:127], v[138:141], v[224:227], v[124:127]
	v_mfma_f32_16x16x32_bf16 v[120:123], v[146:149], v[224:227], v[120:123]
	v_mfma_f32_16x16x32_bf16 v[108:111], v[138:141], v[232:235], v[108:111]
	v_mfma_f32_16x16x32_bf16 v[96:99], v[146:149], v[232:235], v[96:99]
	v_mfma_f32_16x16x32_bf16 v[92:95], v[138:141], v[240:243], v[92:95]
	v_mfma_f32_16x16x32_bf16 v[80:83], v[146:149], v[240:243], v[80:83]
	v_mfma_f32_16x16x32_bf16 v[76:79], v[138:141], v[248:251], v[76:79]
	v_mfma_f32_16x16x32_bf16 v[64:67], v[146:149], v[248:251], v[64:67]
	s_setprio 0
	s_setprio 1
	v_mfma_f32_16x16x32_bf16 v[104:107], v[204:207], v[220:223], 0
	v_mfma_f32_16x16x32_bf16 v[100:103], v[212:215], v[220:223], 0
	v_mfma_f32_16x16x32_bf16 v[88:91], v[204:207], v[228:231], 0
	v_mfma_f32_16x16x32_bf16 v[84:87], v[212:215], v[228:231], 0
	v_mfma_f32_16x16x32_bf16 v[72:75], v[204:207], v[236:239], 0
	v_mfma_f32_16x16x32_bf16 v[68:71], v[212:215], v[236:239], 0
	v_mfma_f32_16x16x32_bf16 v[60:63], v[204:207], v[244:247], 0
	v_mfma_f32_16x16x32_bf16 v[56:59], v[212:215], v[244:247], 0
	v_mfma_f32_16x16x32_bf16 v[104:107], v[208:211], v[224:227], v[104:107]
	v_mfma_f32_16x16x32_bf16 v[100:103], v[216:219], v[224:227], v[100:103]
	v_mfma_f32_16x16x32_bf16 v[88:91], v[208:211], v[232:235], v[88:91]
	v_mfma_f32_16x16x32_bf16 v[84:87], v[216:219], v[232:235], v[84:87]
	v_mfma_f32_16x16x32_bf16 v[72:75], v[208:211], v[240:243], v[72:75]
	v_mfma_f32_16x16x32_bf16 v[68:71], v[216:219], v[240:243], v[68:71]
	v_mfma_f32_16x16x32_bf16 v[60:63], v[208:211], v[248:251], v[60:63]
	v_mfma_f32_16x16x32_bf16 v[56:59], v[216:219], v[248:251], v[56:59]
	s_setprio 0
	s_barrier
	s_add_i32 s65, s58, s46
	s_add_u32 s74, s38, 0x80
	s_addc_u32 s75, s39, 0
	s_mov_b32 m0, s65
	ds_read_b128 v[220:223], v201 offset:16384
	ds_read_b128 v[224:227], v201 offset:17408
	ds_read_b128 v[228:231], v201 offset:18432
	ds_read_b128 v[232:235], v201 offset:19456
	ds_read_b128 v[236:239], v201 offset:20480
	ds_read_b128 v[240:243], v201 offset:21504
	ds_read_b128 v[244:247], v201 offset:22528
	ds_read_b128 v[248:251], v201 offset:23552
	global_load_lds_dwordx4 v154, s[38:39]
	s_add_i32 m0, s65, 0x2000
	s_add_u32 s66, s38, 0x80000
	s_addc_u32 s67, s39, 0
	s_add_i32 s65, s59, s46
	global_load_lds_dwordx4 v158, s[38:39]
	s_mov_b32 m0, s65
	s_nop 0
	global_load_lds_dwordx4 v154, s[66:67]
	s_add_i32 m0, s65, 0x2000
	s_nop 0
	global_load_lds_dwordx4 v158, s[66:67]
	s_add_u32 s78, s40, 0x80
	s_addc_u32 s79, s41, 0
	s_mov_b32 m0, s47
	s_nop 0
	global_load_lds_dwordx4 v152, s[40:41]
	s_mov_b32 m0, s48
	s_nop 0
	global_load_lds_dwordx4 v156, s[40:41]
	s_waitcnt vmcnt(8)
	s_waitcnt lgkmcnt(0)
	s_barrier
	s_setprio 1
	s_waitcnt lgkmcnt(0)
	v_mfma_f32_16x16x32_bf16 v[52:55], v[134:137], v[220:223], 0
	v_mfma_f32_16x16x32_bf16 v[48:51], v[142:145], v[220:223], 0
	v_mfma_f32_16x16x32_bf16 v[44:47], v[134:137], v[228:231], 0
	v_mfma_f32_16x16x32_bf16 v[32:35], v[142:145], v[228:231], 0
	v_mfma_f32_16x16x32_bf16 v[28:31], v[134:137], v[236:239], 0
	v_mfma_f32_16x16x32_bf16 v[16:19], v[142:145], v[236:239], 0
	v_mfma_f32_16x16x32_bf16 v[116:119], v[134:137], v[244:247], 0
	v_mfma_f32_16x16x32_bf16 v[112:115], v[142:145], v[244:247], 0
	v_mfma_f32_16x16x32_bf16 v[52:55], v[138:141], v[224:227], v[52:55]
	v_mfma_f32_16x16x32_bf16 v[48:51], v[146:149], v[224:227], v[48:51]
	v_mfma_f32_16x16x32_bf16 v[44:47], v[138:141], v[232:235], v[44:47]
	v_mfma_f32_16x16x32_bf16 v[32:35], v[146:149], v[232:235], v[32:35]
	v_mfma_f32_16x16x32_bf16 v[28:31], v[138:141], v[240:243], v[28:31]
	v_mfma_f32_16x16x32_bf16 v[16:19], v[146:149], v[240:243], v[16:19]
	v_mfma_f32_16x16x32_bf16 v[116:119], v[138:141], v[248:251], v[116:119]
	v_mfma_f32_16x16x32_bf16 v[112:115], v[146:149], v[248:251], v[112:115]
	s_setprio 0
	s_setprio 1
	v_mfma_f32_16x16x32_bf16 v[40:43], v[204:207], v[220:223], 0
	v_mfma_f32_16x16x32_bf16 v[36:39], v[212:215], v[220:223], 0
	v_mfma_f32_16x16x32_bf16 v[24:27], v[204:207], v[228:231], 0
	v_mfma_f32_16x16x32_bf16 v[20:23], v[212:215], v[228:231], 0
	v_mfma_f32_16x16x32_bf16 v[12:15], v[204:207], v[236:239], 0
	v_mfma_f32_16x16x32_bf16 v[8:11], v[212:215], v[236:239], 0
	v_mfma_f32_16x16x32_bf16 v[4:7], v[204:207], v[244:247], 0
	v_mfma_f32_16x16x32_bf16 v[0:3], v[212:215], v[244:247], 0
	v_mfma_f32_16x16x32_bf16 v[40:43], v[208:211], v[224:227], v[40:43]
	v_mfma_f32_16x16x32_bf16 v[36:39], v[216:219], v[224:227], v[36:39]
	v_mfma_f32_16x16x32_bf16 v[24:27], v[208:211], v[232:235], v[24:27]
	v_mfma_f32_16x16x32_bf16 v[20:23], v[216:219], v[232:235], v[20:23]
	v_mfma_f32_16x16x32_bf16 v[12:15], v[208:211], v[240:243], v[12:15]
	v_mfma_f32_16x16x32_bf16 v[8:11], v[216:219], v[240:243], v[8:11]
	v_mfma_f32_16x16x32_bf16 v[4:7], v[208:211], v[248:251], v[4:7]
	v_mfma_f32_16x16x32_bf16 v[0:3], v[216:219], v[248:251], v[0:3]
	s_setprio 0
	s_barrier
	s_add_i32 s65, 0, 0x18000
	s_add_i32 s66, 0, 0x1c000
	v_add_u32_e32 v146, s65, v176
	v_add_u32_e32 v160, s66, v176
	ds_read_b128 v[134:137], v146
	ds_read_b128 v[138:141], v146 offset:1024
	ds_read_b128 v[142:145], v146 offset:2048
	ds_read_b128 v[146:149], v146 offset:3072
	ds_read_b128 v[204:207], v160
	ds_read_b128 v[208:211], v160 offset:1024
	ds_read_b128 v[212:215], v160 offset:2048
	ds_read_b128 v[216:219], v160 offset:3072
	s_add_u32 s40, s40, 0x80000
	s_addc_u32 s41, s41, 0
	s_mov_b32 m0, s49
	ds_read_b128 v[220:223], v201 offset:32768
	ds_read_b128 v[224:227], v201 offset:33792
	ds_read_b128 v[228:231], v201 offset:34816
	ds_read_b128 v[232:235], v201 offset:35840
	ds_read_b128 v[236:239], v201 offset:36864
	ds_read_b128 v[240:243], v201 offset:37888
	ds_read_b128 v[244:247], v201 offset:38912
	ds_read_b128 v[248:251], v201 offset:39936
	global_load_lds_dwordx4 v152, s[40:41]
	s_mov_b32 m0, s50
	s_nop 0
	global_load_lds_dwordx4 v156, s[40:41]
	s_waitcnt vmcnt(8)
	s_waitcnt lgkmcnt(0)
	s_barrier
	s_setprio 1
	s_waitcnt lgkmcnt(0)
	v_mfma_f32_16x16x32_bf16 v[124:127], v[134:137], v[220:223], v[124:127]
	v_mfma_f32_16x16x32_bf16 v[120:123], v[142:145], v[220:223], v[120:123]
	v_mfma_f32_16x16x32_bf16 v[108:111], v[134:137], v[228:231], v[108:111]
	v_mfma_f32_16x16x32_bf16 v[96:99], v[142:145], v[228:231], v[96:99]
	v_mfma_f32_16x16x32_bf16 v[92:95], v[134:137], v[236:239], v[92:95]
	v_mfma_f32_16x16x32_bf16 v[80:83], v[142:145], v[236:239], v[80:83]
	v_mfma_f32_16x16x32_bf16 v[76:79], v[134:137], v[244:247], v[76:79]
	v_mfma_f32_16x16x32_bf16 v[64:67], v[142:145], v[244:247], v[64:67]
	v_mfma_f32_16x16x32_bf16 v[124:127], v[138:141], v[224:227], v[124:127]
	v_mfma_f32_16x16x32_bf16 v[120:123], v[146:149], v[224:227], v[120:123]
	v_mfma_f32_16x16x32_bf16 v[108:111], v[138:141], v[232:235], v[108:111]
	v_mfma_f32_16x16x32_bf16 v[96:99], v[146:149], v[232:235], v[96:99]
	v_mfma_f32_16x16x32_bf16 v[92:95], v[138:141], v[240:243], v[92:95]
	v_mfma_f32_16x16x32_bf16 v[80:83], v[146:149], v[240:243], v[80:83]
	v_mfma_f32_16x16x32_bf16 v[76:79], v[138:141], v[248:251], v[76:79]
	v_mfma_f32_16x16x32_bf16 v[64:67], v[146:149], v[248:251], v[64:67]
	s_setprio 0
	s_setprio 1
	v_mfma_f32_16x16x32_bf16 v[104:107], v[204:207], v[220:223], v[104:107]
	v_mfma_f32_16x16x32_bf16 v[100:103], v[212:215], v[220:223], v[100:103]
	v_mfma_f32_16x16x32_bf16 v[88:91], v[204:207], v[228:231], v[88:91]
	v_mfma_f32_16x16x32_bf16 v[84:87], v[212:215], v[228:231], v[84:87]
	v_mfma_f32_16x16x32_bf16 v[72:75], v[204:207], v[236:239], v[72:75]
	v_mfma_f32_16x16x32_bf16 v[68:71], v[212:215], v[236:239], v[68:71]
	v_mfma_f32_16x16x32_bf16 v[60:63], v[204:207], v[244:247], v[60:63]
	v_mfma_f32_16x16x32_bf16 v[56:59], v[212:215], v[244:247], v[56:59]
	v_mfma_f32_16x16x32_bf16 v[104:107], v[208:211], v[224:227], v[104:107]
	v_mfma_f32_16x16x32_bf16 v[100:103], v[216:219], v[224:227], v[100:103]
	v_mfma_f32_16x16x32_bf16 v[88:91], v[208:211], v[232:235], v[88:91]
	v_mfma_f32_16x16x32_bf16 v[84:87], v[216:219], v[232:235], v[84:87]
	v_mfma_f32_16x16x32_bf16 v[72:75], v[208:211], v[240:243], v[72:75]
	v_mfma_f32_16x16x32_bf16 v[68:71], v[216:219], v[240:243], v[68:71]
	v_mfma_f32_16x16x32_bf16 v[60:63], v[208:211], v[248:251], v[60:63]
	v_mfma_f32_16x16x32_bf16 v[56:59], v[216:219], v[248:251], v[56:59]
	s_setprio 0
	s_barrier
	s_add_i32 s40, s65, s46
	s_mov_b32 m0, s40
	ds_read_b128 v[220:223], v201 offset:49152
	ds_read_b128 v[224:227], v201 offset:50176
	ds_read_b128 v[228:231], v201 offset:51200
	ds_read_b128 v[232:235], v201 offset:52224
	ds_read_b128 v[236:239], v201 offset:53248
	ds_read_b128 v[240:243], v201 offset:54272
	ds_read_b128 v[244:247], v201 offset:55296
	ds_read_b128 v[248:251], v201 offset:56320
	global_load_lds_dwordx4 v154, s[74:75]
	s_add_i32 m0, s40, 0x2000
	s_add_u32 s38, s38, 0x80080
	s_addc_u32 s39, s39, 0
	s_add_i32 s40, s66, s46
	global_load_lds_dwordx4 v158, s[74:75]
	s_mov_b32 m0, s40
	s_nop 0
	global_load_lds_dwordx4 v154, s[38:39]
	s_add_i32 m0, s40, 0x2000
	s_nop 0
	global_load_lds_dwordx4 v158, s[38:39]
	s_mov_b32 m0, s53
	s_nop 0
	global_load_lds_dwordx4 v152, s[78:79]
	s_mov_b32 m0, s54
	s_nop 0
	global_load_lds_dwordx4 v156, s[78:79]
	s_waitcnt vmcnt(8)
	s_waitcnt lgkmcnt(0)
	s_barrier
	s_setprio 1
	s_waitcnt lgkmcnt(0)
	v_mfma_f32_16x16x32_bf16 v[52:55], v[134:137], v[220:223], v[52:55]
	v_mfma_f32_16x16x32_bf16 v[48:51], v[142:145], v[220:223], v[48:51]
	v_mfma_f32_16x16x32_bf16 v[44:47], v[134:137], v[228:231], v[44:47]
	v_mfma_f32_16x16x32_bf16 v[32:35], v[142:145], v[228:231], v[32:35]
	v_mfma_f32_16x16x32_bf16 v[28:31], v[134:137], v[236:239], v[28:31]
	v_mfma_f32_16x16x32_bf16 v[16:19], v[142:145], v[236:239], v[16:19]
	v_mfma_f32_16x16x32_bf16 v[116:119], v[134:137], v[244:247], v[116:119]
	v_mfma_f32_16x16x32_bf16 v[112:115], v[142:145], v[244:247], v[112:115]
	v_mfma_f32_16x16x32_bf16 v[52:55], v[138:141], v[224:227], v[52:55]
	v_mfma_f32_16x16x32_bf16 v[48:51], v[146:149], v[224:227], v[48:51]
	v_mfma_f32_16x16x32_bf16 v[44:47], v[138:141], v[232:235], v[44:47]
	v_mfma_f32_16x16x32_bf16 v[32:35], v[146:149], v[232:235], v[32:35]
	v_mfma_f32_16x16x32_bf16 v[28:31], v[138:141], v[240:243], v[28:31]
	v_mfma_f32_16x16x32_bf16 v[16:19], v[146:149], v[240:243], v[16:19]
	v_mfma_f32_16x16x32_bf16 v[116:119], v[138:141], v[248:251], v[116:119]
	v_mfma_f32_16x16x32_bf16 v[112:115], v[146:149], v[248:251], v[112:115]
	s_setprio 0
	s_setprio 1
	v_mfma_f32_16x16x32_bf16 v[40:43], v[204:207], v[220:223], v[40:43]
	v_mfma_f32_16x16x32_bf16 v[36:39], v[212:215], v[220:223], v[36:39]
	v_mfma_f32_16x16x32_bf16 v[24:27], v[204:207], v[228:231], v[24:27]
	v_mfma_f32_16x16x32_bf16 v[20:23], v[212:215], v[228:231], v[20:23]
	v_mfma_f32_16x16x32_bf16 v[12:15], v[204:207], v[236:239], v[12:15]
	v_mfma_f32_16x16x32_bf16 v[8:11], v[212:215], v[236:239], v[8:11]
	v_mfma_f32_16x16x32_bf16 v[4:7], v[204:207], v[244:247], v[4:7]
	v_mfma_f32_16x16x32_bf16 v[0:3], v[212:215], v[244:247], v[0:3]
	v_mfma_f32_16x16x32_bf16 v[40:43], v[208:211], v[224:227], v[40:43]
	v_mfma_f32_16x16x32_bf16 v[36:39], v[216:219], v[224:227], v[36:39]
	v_mfma_f32_16x16x32_bf16 v[24:27], v[208:211], v[232:235], v[24:27]
	v_mfma_f32_16x16x32_bf16 v[20:23], v[216:219], v[232:235], v[20:23]
	v_mfma_f32_16x16x32_bf16 v[12:15], v[208:211], v[240:243], v[12:15]
	v_mfma_f32_16x16x32_bf16 v[8:11], v[216:219], v[240:243], v[8:11]
	v_mfma_f32_16x16x32_bf16 v[4:7], v[208:211], v[248:251], v[4:7]
	v_mfma_f32_16x16x32_bf16 v[0:3], v[216:219], v[248:251], v[0:3]
	s_setprio 0
	s_barrier
	s_add_i32 s64, s64, 2
	s_add_u32 s36, s36, 0x100
	s_addc_u32 s37, s37, 0
	s_cmp_gt_u32 s64, 29
	s_cbranch_scc1 .LBB0_321
	s_branch .LBB0_319

.LBB0_526:
	s_nop 0
	s_cmp_lt_i32 s92, 3
	s_cselect_b64 s[2:3], -1, 0
	s_cmp_gt_i32 s93, 2
	s_cselect_b64 s[4:5], -1, 0
	v_writelane_b32 v254, s69, 28
	s_and_b64 s[2:3], s[2:3], s[4:5]
	v_writelane_b32 v254, s68, 29
	s_mov_b64 s[4:5], s[92:93]
	v_writelane_b32 v254, s4, 30
	s_andn2_b64 vcc, exec, s[2:3]
	s_nop 0
	v_writelane_b32 v254, s5, 31
	v_writelane_b32 v254, s6, 32
	v_writelane_b32 v254, s7, 33
	s_cbranch_vccnz .LBB0_863
	v_readlane_b32 s16, v254, 16
	v_mov_b32_e32 v0, 0
	v_readlane_b32 s22, v254, 22
	v_readlane_b32 s23, v254, 23
	s_andn2_b64 vcc, exec, s[10:11]
	v_readlane_b32 s17, v254, 17
	v_readlane_b32 s18, v254, 18
	v_readlane_b32 s19, v254, 19
	v_readlane_b32 s20, v254, 20
	global_load_dword v160, v0, s[22:23]
	v_readlane_b32 s21, v254, 21
	s_cbranch_vccnz .LBB0_529
	v_mbcnt_lo_u32_b32 v0, -1, 0
	v_mbcnt_hi_u32_b32 v0, -1, v0
	s_mov_b32 s0, 0x42c80000
	s_waitcnt lgkmcnt(0)
	v_ashrrev_i32_e32 v1, 31, v0
	v_lshlrev_b64 v[0:1], 2, v[0:1]
	v_lshl_add_u64 v[2:3], s[12:13], 0, v[0:1]
	global_load_dword v4, v[2:3], off
	global_load_dword v5, v[2:3], off offset:256
	v_lshl_add_u64 v[0:1], s[14:15], 0, v[0:1]
	global_load_dword v2, v[0:1], off offset:256
	global_load_dword v3, v[0:1], off
	v_mbcnt_lo_u32_b32 v0, -1, 0
	v_mbcnt_hi_u32_b32 v0, -1, v0
	v_and_b32_e32 v1, 64, v0
	v_xor_b32_e32 v6, 1, v0
	v_add_u32_e32 v1, 64, v1
	v_cmp_lt_i32_e32 vcc, v6, v1
	v_xor_b32_e32 v7, 2, v0
	v_xor_b32_e32 v8, 4, v0
	v_cndmask_b32_e32 v6, v0, v6, vcc
	v_lshlrev_b32_e32 v6, 2, v6
	v_cmp_lt_i32_e32 vcc, v7, v1
	v_xor_b32_e32 v9, 8, v0
	v_xor_b32_e32 v10, 16, v0
	v_xor_b32_e32 v11, 32, v0
	s_waitcnt vmcnt(0)
	v_max_f32_e64 v4, |v4|, |v4|
	v_max_f32_e64 v5, |v5|, |v5|
	v_max_f32_e64 v2, |v2|, |v2|
	v_max_f32_e64 v3, |v3|, |v3|
	v_max_f32_e32 v4, v4, v5
	v_max_f32_e32 v2, v3, v2
	ds_bpermute_b32 v3, v6, v4
	ds_bpermute_b32 v5, v6, v2
	v_cndmask_b32_e32 v6, v0, v7, vcc
	v_lshlrev_b32_e32 v6, 2, v6
	v_cmp_lt_i32_e32 vcc, v8, v1
	s_waitcnt lgkmcnt(1)
	v_max_f32_e32 v3, v3, v3
	s_waitcnt lgkmcnt(0)
	v_max_f32_e32 v5, v5, v5
	v_max_f32_e32 v3, v4, v3
	v_max_f32_e32 v2, v2, v5
	ds_bpermute_b32 v4, v6, v3
	ds_bpermute_b32 v5, v6, v2
	v_cndmask_b32_e32 v6, v0, v8, vcc
	v_lshlrev_b32_e32 v6, 2, v6
	v_cmp_lt_i32_e32 vcc, v9, v1
	s_waitcnt lgkmcnt(1)
	v_max_f32_e32 v4, v4, v4
	s_waitcnt lgkmcnt(0)
	v_max_f32_e32 v5, v5, v5
	v_max_f32_e32 v3, v3, v4
	v_max_f32_e32 v2, v2, v5
	ds_bpermute_b32 v4, v6, v3
	ds_bpermute_b32 v5, v6, v2
	v_cndmask_b32_e32 v6, v0, v9, vcc
	v_lshlrev_b32_e32 v6, 2, v6
	v_cmp_lt_i32_e32 vcc, v10, v1
	s_waitcnt lgkmcnt(1)
	v_max_f32_e32 v4, v4, v4
	s_waitcnt lgkmcnt(0)
	v_max_f32_e32 v5, v5, v5
	v_max_f32_e32 v3, v3, v4
	v_max_f32_e32 v2, v2, v5
	ds_bpermute_b32 v4, v6, v3
	ds_bpermute_b32 v5, v6, v2
	v_cndmask_b32_e32 v6, v0, v10, vcc
	v_lshlrev_b32_e32 v6, 2, v6
	v_cmp_lt_i32_e32 vcc, v11, v1
	s_waitcnt lgkmcnt(1)
	v_max_f32_e32 v4, v4, v4
	s_waitcnt lgkmcnt(0)
	v_max_f32_e32 v5, v5, v5
	v_max_f32_e32 v3, v3, v4
	v_max_f32_e32 v2, v2, v5
	ds_bpermute_b32 v4, v6, v3
	ds_bpermute_b32 v5, v6, v2
	v_cndmask_b32_e32 v0, v0, v11, vcc
	v_lshlrev_b32_e32 v0, 2, v0
	s_waitcnt lgkmcnt(1)
	v_max_f32_e32 v1, v4, v4
	s_waitcnt lgkmcnt(0)
	v_max_f32_e32 v4, v5, v5
	v_max_f32_e32 v1, v3, v1
	v_max_f32_e32 v2, v2, v4
	ds_bpermute_b32 v3, v0, v1
	ds_bpermute_b32 v0, v0, v2
	s_waitcnt lgkmcnt(1)
	v_max_f32_e32 v3, v3, v3
	s_waitcnt lgkmcnt(0)
	v_max_f32_e32 v0, v0, v0
	v_max_f32_e32 v1, v1, v3
	v_max_f32_e32 v0, v2, v0
	v_mul_f32_e32 v1, 0x430147ae, v1
	v_mul_f32_e32 v0, v0, v1
	v_mul_f32_e32 v0, 0x3db504f3, v0
	v_mul_f32_e32 v0, 0x3fb8aa3b, v0
	v_cmp_ge_f32_e32 vcc, s0, v0
	s_nop 1
	v_cndmask_b32_e64 v0, 0, 1, vcc
	s_nop 0
	v_readfirstlane_b32 s0, v0
	s_bitcmp1_b32 s0, 0
	s_cselect_b64 s[0:1], -1, 0

.LBB0_863:
	s_nop 0
	s_cmp_lt_i32 s92, 4
	s_cselect_b64 s[0:1], -1, 0
	s_cmp_gt_i32 s93, 3
	s_cselect_b64 s[2:3], -1, 0
	s_and_b64 s[0:1], s[0:1], s[2:3]
	s_andn2_b64 vcc, exec, s[0:1]
	s_cbranch_vccnz .LBB0_989
	v_readlane_b32 s0, v254, 24
	s_and_b32 s33, s0, 0xffffffc0
	v_mbcnt_lo_u32_b32 v8, -1, 0
	v_mbcnt_hi_u32_b32 v8, -1, v8
	s_cmpk_lt_i32 s69, 0x200
	v_add_u32_e32 v0, s33, v8
	s_cselect_b64 s[0:1], -1, 0
	s_cmpk_gt_i32 s69, 0x1ff
	v_readfirstlane_b32 s4, v0
	s_cbranch_scc0 .LBB0_867
	s_andn2_b64 vcc, exec, s[0:1]
	s_cbranch_vccz .LBB0_872

.LBB0_883:
	s_ashr_i32 s19, s18, 31
	s_lshl_b64 s[20:21], s[18:19], 20
	s_add_u32 s20, s34, s20
	s_addc_u32 s21, s35, s21
	s_and_b64 s[22:23], s[4:5], exec
	s_cselect_b32 s7, s21, s27
	s_cselect_b32 s19, s20, s26
	s_ashr_i32 s17, s16, 31
	s_lshl_b64 s[22:23], s[16:17], 20
	s_add_u32 s22, s36, s22
	s_addc_u32 s23, s37, s23
	s_and_b64 s[30:31], s[4:5], exec
	s_cselect_b32 s17, s23, s29
	s_cselect_b32 s25, s22, s28
	s_add_u32 s26, s26, 0x80080
	s_addc_u32 s27, s27, 0
	s_add_u32 s52, s28, 0x100
	s_addc_u32 s53, s29, 0
	s_mov_b32 s54, -2
	ds_read_b128 v[144:147], v174
	ds_read_b128 v[178:181], v174 offset:1024
	ds_read_b128 v[182:185], v174 offset:2048
	ds_read_b128 v[186:189], v174 offset:3072
	ds_read_b128 v[190:193], v175
	ds_read_b128 v[194:197], v175 offset:1024
	ds_read_b128 v[198:201], v175 offset:2048
	ds_read_b128 v[202:205], v175 offset:3072
	s_add_u32 s28, s26, 0xfff80080
	s_addc_u32 s29, s27, -1
	s_cmp_eq_u32 s54, 28
	s_cselect_b32 s31, s7, s29
	s_cselect_b32 s30, s19, s28
	s_cselect_b32 s29, s17, s53
	s_cselect_b32 s28, s25, s52
	s_add_i32 m0, s39, 0xc000
	ds_read_b128 v[206:209], v176
	ds_read_b128 v[210:213], v176 offset:1024
	ds_read_b128 v[214:217], v176 offset:2048
	ds_read_b128 v[218:221], v176 offset:3072
	ds_read_b128 v[222:225], v176 offset:4096
	ds_read_b128 v[226:229], v176 offset:5120
	ds_read_b128 v[230:233], v176 offset:6144
	ds_read_b128 v[234:237], v176 offset:7168
	global_load_lds_dwordx4 v136, s[26:27]
	s_add_i32 m0, s39, 0xe000
	s_nop 0
	global_load_lds_dwordx4 v138, s[26:27]
	s_waitcnt vmcnt(8)
	s_waitcnt lgkmcnt(0)
	s_barrier
	s_setprio 1
	s_waitcnt lgkmcnt(0)
	v_mfma_f32_16x16x32_bf16 v[124:127], v[144:147], v[206:209], 0
	v_mfma_f32_16x16x32_bf16 v[120:123], v[182:185], v[206:209], 0
	v_mfma_f32_16x16x32_bf16 v[108:111], v[144:147], v[214:217], 0
	v_mfma_f32_16x16x32_bf16 v[104:107], v[182:185], v[214:217], 0
	v_mfma_f32_16x16x32_bf16 v[92:95], v[144:147], v[222:225], 0
	v_mfma_f32_16x16x32_bf16 v[88:91], v[182:185], v[222:225], 0
	v_mfma_f32_16x16x32_bf16 v[76:79], v[144:147], v[230:233], 0
	v_mfma_f32_16x16x32_bf16 v[72:75], v[182:185], v[230:233], 0
	v_mfma_f32_16x16x32_bf16 v[124:127], v[178:181], v[210:213], v[124:127]
	v_mfma_f32_16x16x32_bf16 v[120:123], v[186:189], v[210:213], v[120:123]
	v_mfma_f32_16x16x32_bf16 v[108:111], v[178:181], v[218:221], v[108:111]
	v_mfma_f32_16x16x32_bf16 v[104:107], v[186:189], v[218:221], v[104:107]
	v_mfma_f32_16x16x32_bf16 v[92:95], v[178:181], v[226:229], v[92:95]
	v_mfma_f32_16x16x32_bf16 v[88:91], v[186:189], v[226:229], v[88:91]
	v_mfma_f32_16x16x32_bf16 v[76:79], v[178:181], v[234:237], v[76:79]
	v_mfma_f32_16x16x32_bf16 v[72:75], v[186:189], v[234:237], v[72:75]
	s_setprio 0
	s_setprio 1
	v_mfma_f32_16x16x32_bf16 v[116:119], v[190:193], v[206:209], 0
	v_mfma_f32_16x16x32_bf16 v[112:115], v[198:201], v[206:209], 0
	v_mfma_f32_16x16x32_bf16 v[100:103], v[190:193], v[214:217], 0
	v_mfma_f32_16x16x32_bf16 v[96:99], v[198:201], v[214:217], 0
	v_mfma_f32_16x16x32_bf16 v[84:87], v[190:193], v[222:225], 0
	v_mfma_f32_16x16x32_bf16 v[80:83], v[198:201], v[222:225], 0
	v_mfma_f32_16x16x32_bf16 v[68:71], v[190:193], v[230:233], 0
	v_mfma_f32_16x16x32_bf16 v[64:67], v[198:201], v[230:233], 0
	v_mfma_f32_16x16x32_bf16 v[116:119], v[194:197], v[210:213], v[116:119]
	v_mfma_f32_16x16x32_bf16 v[112:115], v[202:205], v[210:213], v[112:115]
	v_mfma_f32_16x16x32_bf16 v[100:103], v[194:197], v[218:221], v[100:103]
	v_mfma_f32_16x16x32_bf16 v[96:99], v[202:205], v[218:221], v[96:99]
	v_mfma_f32_16x16x32_bf16 v[84:87], v[194:197], v[226:229], v[84:87]
	v_mfma_f32_16x16x32_bf16 v[80:83], v[202:205], v[226:229], v[80:83]
	v_mfma_f32_16x16x32_bf16 v[68:71], v[194:197], v[234:237], v[68:71]
	v_mfma_f32_16x16x32_bf16 v[64:67], v[202:205], v[234:237], v[64:67]
	s_setprio 0
	s_barrier
	s_add_i32 s55, s50, s38
	s_add_u32 s70, s28, 0x80
	s_addc_u32 s71, s29, 0
	s_mov_b32 m0, s55
	ds_read_b128 v[206:209], v176 offset:16384
	ds_read_b128 v[210:213], v176 offset:17408
	ds_read_b128 v[214:217], v176 offset:18432
	ds_read_b128 v[218:221], v176 offset:19456
	ds_read_b128 v[222:225], v176 offset:20480
	ds_read_b128 v[226:229], v176 offset:21504
	ds_read_b128 v[230:233], v176 offset:22528
	ds_read_b128 v[234:237], v176 offset:23552
	global_load_lds_dwordx4 v130, s[28:29]
	s_add_i32 m0, s55, 0x2000
	s_add_u32 s56, s28, 0x80000
	s_addc_u32 s57, s29, 0
	s_add_i32 s55, s51, s38
	global_load_lds_dwordx4 v134, s[28:29]
	s_mov_b32 m0, s55
	s_nop 0
	global_load_lds_dwordx4 v130, s[56:57]
	s_add_i32 m0, s55, 0x2000
	s_nop 0
	global_load_lds_dwordx4 v134, s[56:57]
	s_add_u32 s74, s30, 0x80
	s_addc_u32 s75, s31, 0
	s_mov_b32 m0, s39
	s_nop 0
	global_load_lds_dwordx4 v128, s[30:31]
	s_mov_b32 m0, s40
	s_nop 0
	global_load_lds_dwordx4 v132, s[30:31]
	s_waitcnt vmcnt(8)
	s_waitcnt lgkmcnt(0)
	s_barrier
	s_setprio 1
	s_waitcnt lgkmcnt(0)
	v_mfma_f32_16x16x32_bf16 v[60:63], v[144:147], v[206:209], 0
	v_mfma_f32_16x16x32_bf16 v[56:59], v[182:185], v[206:209], 0
	v_mfma_f32_16x16x32_bf16 v[44:47], v[144:147], v[214:217], 0
	v_mfma_f32_16x16x32_bf16 v[40:43], v[182:185], v[214:217], 0
	v_mfma_f32_16x16x32_bf16 v[28:31], v[144:147], v[222:225], 0
	v_mfma_f32_16x16x32_bf16 v[24:27], v[182:185], v[222:225], 0
	v_mfma_f32_16x16x32_bf16 v[12:15], v[144:147], v[230:233], 0
	v_mfma_f32_16x16x32_bf16 v[8:11], v[182:185], v[230:233], 0
	v_mfma_f32_16x16x32_bf16 v[60:63], v[178:181], v[210:213], v[60:63]
	v_mfma_f32_16x16x32_bf16 v[56:59], v[186:189], v[210:213], v[56:59]
	v_mfma_f32_16x16x32_bf16 v[44:47], v[178:181], v[218:221], v[44:47]
	v_mfma_f32_16x16x32_bf16 v[40:43], v[186:189], v[218:221], v[40:43]
	v_mfma_f32_16x16x32_bf16 v[28:31], v[178:181], v[226:229], v[28:31]
	v_mfma_f32_16x16x32_bf16 v[24:27], v[186:189], v[226:229], v[24:27]
	v_mfma_f32_16x16x32_bf16 v[12:15], v[178:181], v[234:237], v[12:15]
	v_mfma_f32_16x16x32_bf16 v[8:11], v[186:189], v[234:237], v[8:11]
	s_setprio 0
	s_setprio 1
	v_mfma_f32_16x16x32_bf16 v[52:55], v[190:193], v[206:209], 0
	v_mfma_f32_16x16x32_bf16 v[48:51], v[198:201], v[206:209], 0
	v_mfma_f32_16x16x32_bf16 v[36:39], v[190:193], v[214:217], 0
	v_mfma_f32_16x16x32_bf16 v[32:35], v[198:201], v[214:217], 0
	v_mfma_f32_16x16x32_bf16 v[20:23], v[190:193], v[222:225], 0
	v_mfma_f32_16x16x32_bf16 v[16:19], v[198:201], v[222:225], 0
	v_mfma_f32_16x16x32_bf16 v[4:7], v[190:193], v[230:233], 0
	v_mfma_f32_16x16x32_bf16 v[0:3], v[198:201], v[230:233], 0
	v_mfma_f32_16x16x32_bf16 v[52:55], v[194:197], v[210:213], v[52:55]
	v_mfma_f32_16x16x32_bf16 v[48:51], v[202:205], v[210:213], v[48:51]
	v_mfma_f32_16x16x32_bf16 v[36:39], v[194:197], v[218:221], v[36:39]
	v_mfma_f32_16x16x32_bf16 v[32:35], v[202:205], v[218:221], v[32:35]
	v_mfma_f32_16x16x32_bf16 v[20:23], v[194:197], v[226:229], v[20:23]
	v_mfma_f32_16x16x32_bf16 v[16:19], v[202:205], v[226:229], v[16:19]
	v_mfma_f32_16x16x32_bf16 v[4:7], v[194:197], v[234:237], v[4:7]
	v_mfma_f32_16x16x32_bf16 v[0:3], v[202:205], v[234:237], v[0:3]
	s_setprio 0
	s_barrier
	s_add_i32 s55, 0, 0x18000
	v_add_u32_e32 v177, s55, v149
	s_add_i32 s56, 0, 0x1c000
	ds_read_b128 v[144:147], v177
	ds_read_b128 v[178:181], v177 offset:1024
	ds_read_b128 v[182:185], v177 offset:2048
	ds_read_b128 v[186:189], v177 offset:3072
	v_add_u32_e32 v177, s56, v149
	ds_read_b128 v[190:193], v177
	ds_read_b128 v[194:197], v177 offset:1024
	ds_read_b128 v[198:201], v177 offset:2048
	ds_read_b128 v[202:205], v177 offset:3072
	s_add_u32 s30, s30, 0x80000
	s_addc_u32 s31, s31, 0
	s_mov_b32 m0, s41
	ds_read_b128 v[206:209], v176 offset:32768
	ds_read_b128 v[210:213], v176 offset:33792
	ds_read_b128 v[214:217], v176 offset:34816
	ds_read_b128 v[218:221], v176 offset:35840
	ds_read_b128 v[222:225], v176 offset:36864
	ds_read_b128 v[226:229], v176 offset:37888
	ds_read_b128 v[230:233], v176 offset:38912
	ds_read_b128 v[234:237], v176 offset:39936
	global_load_lds_dwordx4 v128, s[30:31]
	s_mov_b32 m0, s42
	s_nop 0
	global_load_lds_dwordx4 v132, s[30:31]
	s_waitcnt vmcnt(8)
	s_waitcnt lgkmcnt(0)
	s_barrier
	s_setprio 1
	s_waitcnt lgkmcnt(0)
	v_mfma_f32_16x16x32_bf16 v[124:127], v[144:147], v[206:209], v[124:127]
	v_mfma_f32_16x16x32_bf16 v[120:123], v[182:185], v[206:209], v[120:123]
	v_mfma_f32_16x16x32_bf16 v[108:111], v[144:147], v[214:217], v[108:111]
	v_mfma_f32_16x16x32_bf16 v[104:107], v[182:185], v[214:217], v[104:107]
	v_mfma_f32_16x16x32_bf16 v[92:95], v[144:147], v[222:225], v[92:95]
	v_mfma_f32_16x16x32_bf16 v[88:91], v[182:185], v[222:225], v[88:91]
	v_mfma_f32_16x16x32_bf16 v[76:79], v[144:147], v[230:233], v[76:79]
	v_mfma_f32_16x16x32_bf16 v[72:75], v[182:185], v[230:233], v[72:75]
	v_mfma_f32_16x16x32_bf16 v[124:127], v[178:181], v[210:213], v[124:127]
	v_mfma_f32_16x16x32_bf16 v[120:123], v[186:189], v[210:213], v[120:123]
	v_mfma_f32_16x16x32_bf16 v[108:111], v[178:181], v[218:221], v[108:111]
	v_mfma_f32_16x16x32_bf16 v[104:107], v[186:189], v[218:221], v[104:107]
	v_mfma_f32_16x16x32_bf16 v[92:95], v[178:181], v[226:229], v[92:95]
	v_mfma_f32_16x16x32_bf16 v[88:91], v[186:189], v[226:229], v[88:91]
	v_mfma_f32_16x16x32_bf16 v[76:79], v[178:181], v[234:237], v[76:79]
	v_mfma_f32_16x16x32_bf16 v[72:75], v[186:189], v[234:237], v[72:75]
	s_setprio 0
	s_setprio 1
	v_mfma_f32_16x16x32_bf16 v[116:119], v[190:193], v[206:209], v[116:119]
	v_mfma_f32_16x16x32_bf16 v[112:115], v[198:201], v[206:209], v[112:115]
	v_mfma_f32_16x16x32_bf16 v[100:103], v[190:193], v[214:217], v[100:103]
	v_mfma_f32_16x16x32_bf16 v[96:99], v[198:201], v[214:217], v[96:99]
	v_mfma_f32_16x16x32_bf16 v[84:87], v[190:193], v[222:225], v[84:87]
	v_mfma_f32_16x16x32_bf16 v[80:83], v[198:201], v[222:225], v[80:83]
	v_mfma_f32_16x16x32_bf16 v[68:71], v[190:193], v[230:233], v[68:71]
	v_mfma_f32_16x16x32_bf16 v[64:67], v[198:201], v[230:233], v[64:67]
	v_mfma_f32_16x16x32_bf16 v[116:119], v[194:197], v[210:213], v[116:119]
	v_mfma_f32_16x16x32_bf16 v[112:115], v[202:205], v[210:213], v[112:115]
	v_mfma_f32_16x16x32_bf16 v[100:103], v[194:197], v[218:221], v[100:103]
	v_mfma_f32_16x16x32_bf16 v[96:99], v[202:205], v[218:221], v[96:99]
	v_mfma_f32_16x16x32_bf16 v[84:87], v[194:197], v[226:229], v[84:87]
	v_mfma_f32_16x16x32_bf16 v[80:83], v[202:205], v[226:229], v[80:83]
	v_mfma_f32_16x16x32_bf16 v[68:71], v[194:197], v[234:237], v[68:71]
	v_mfma_f32_16x16x32_bf16 v[64:67], v[202:205], v[234:237], v[64:67]
	s_setprio 0
	s_barrier
	s_add_i32 s30, s55, s38
	s_mov_b32 m0, s30
	ds_read_b128 v[206:209], v176 offset:49152
	ds_read_b128 v[210:213], v176 offset:50176
	ds_read_b128 v[214:217], v176 offset:51200
	ds_read_b128 v[218:221], v176 offset:52224
	ds_read_b128 v[222:225], v176 offset:53248
	ds_read_b128 v[226:229], v176 offset:54272
	ds_read_b128 v[230:233], v176 offset:55296
	ds_read_b128 v[234:237], v176 offset:56320
	global_load_lds_dwordx4 v130, s[70:71]
	s_add_i32 m0, s30, 0x2000
	s_add_u32 s28, s28, 0x80080
	s_addc_u32 s29, s29, 0
	s_add_i32 s30, s56, s38
	global_load_lds_dwordx4 v134, s[70:71]
	s_mov_b32 m0, s30
	s_nop 0
	global_load_lds_dwordx4 v130, s[28:29]
	s_add_i32 m0, s30, 0x2000
	s_nop 0
	global_load_lds_dwordx4 v134, s[28:29]
	s_mov_b32 m0, s46
	s_nop 0
	global_load_lds_dwordx4 v128, s[74:75]
	s_mov_b32 m0, s47
	s_nop 0
	global_load_lds_dwordx4 v132, s[74:75]
	s_waitcnt vmcnt(8)
	s_waitcnt lgkmcnt(0)
	s_barrier
	s_setprio 1
	s_waitcnt lgkmcnt(0)
	v_mfma_f32_16x16x32_bf16 v[60:63], v[144:147], v[206:209], v[60:63]
	v_mfma_f32_16x16x32_bf16 v[56:59], v[182:185], v[206:209], v[56:59]
	v_mfma_f32_16x16x32_bf16 v[44:47], v[144:147], v[214:217], v[44:47]
	v_mfma_f32_16x16x32_bf16 v[40:43], v[182:185], v[214:217], v[40:43]
	v_mfma_f32_16x16x32_bf16 v[28:31], v[144:147], v[222:225], v[28:31]
	v_mfma_f32_16x16x32_bf16 v[24:27], v[182:185], v[222:225], v[24:27]
	v_mfma_f32_16x16x32_bf16 v[12:15], v[144:147], v[230:233], v[12:15]
	v_mfma_f32_16x16x32_bf16 v[8:11], v[182:185], v[230:233], v[8:11]
	v_mfma_f32_16x16x32_bf16 v[60:63], v[178:181], v[210:213], v[60:63]
	v_mfma_f32_16x16x32_bf16 v[56:59], v[186:189], v[210:213], v[56:59]
	v_mfma_f32_16x16x32_bf16 v[44:47], v[178:181], v[218:221], v[44:47]
	v_mfma_f32_16x16x32_bf16 v[40:43], v[186:189], v[218:221], v[40:43]
	v_mfma_f32_16x16x32_bf16 v[28:31], v[178:181], v[226:229], v[28:31]
	v_mfma_f32_16x16x32_bf16 v[24:27], v[186:189], v[226:229], v[24:27]
	v_mfma_f32_16x16x32_bf16 v[12:15], v[178:181], v[234:237], v[12:15]
	v_mfma_f32_16x16x32_bf16 v[8:11], v[186:189], v[234:237], v[8:11]
	s_setprio 0
	s_setprio 1
	v_mfma_f32_16x16x32_bf16 v[52:55], v[190:193], v[206:209], v[52:55]
	v_mfma_f32_16x16x32_bf16 v[48:51], v[198:201], v[206:209], v[48:51]
	v_mfma_f32_16x16x32_bf16 v[36:39], v[190:193], v[214:217], v[36:39]
	v_mfma_f32_16x16x32_bf16 v[32:35], v[198:201], v[214:217], v[32:35]
	v_mfma_f32_16x16x32_bf16 v[20:23], v[190:193], v[222:225], v[20:23]
	v_mfma_f32_16x16x32_bf16 v[16:19], v[198:201], v[222:225], v[16:19]
	v_mfma_f32_16x16x32_bf16 v[4:7], v[190:193], v[230:233], v[4:7]
	v_mfma_f32_16x16x32_bf16 v[0:3], v[198:201], v[230:233], v[0:3]
	v_mfma_f32_16x16x32_bf16 v[52:55], v[194:197], v[210:213], v[52:55]
	v_mfma_f32_16x16x32_bf16 v[48:51], v[202:205], v[210:213], v[48:51]
	v_mfma_f32_16x16x32_bf16 v[36:39], v[194:197], v[218:221], v[36:39]
	v_mfma_f32_16x16x32_bf16 v[32:35], v[202:205], v[218:221], v[32:35]
	v_mfma_f32_16x16x32_bf16 v[20:23], v[194:197], v[226:229], v[20:23]
	v_mfma_f32_16x16x32_bf16 v[16:19], v[202:205], v[226:229], v[16:19]
	v_mfma_f32_16x16x32_bf16 v[4:7], v[194:197], v[234:237], v[4:7]
	v_mfma_f32_16x16x32_bf16 v[0:3], v[202:205], v[234:237], v[0:3]
	s_setprio 0
	s_barrier
	s_add_i32 s54, s54, 2
	s_add_u32 s26, s26, 0x100
	s_addc_u32 s27, s27, 0
	s_add_u32 s52, s52, 0x100
	s_addc_u32 s53, s53, 0
	s_cmp_gt_u32 s54, 29
	s_cbranch_scc0 .LBB0_884
	s_branch .Lpeel_after_p3
.LBB0_884:
	ds_read_b128 v[144:147], v174
	ds_read_b128 v[178:181], v174 offset:1024
	ds_read_b128 v[182:185], v174 offset:2048
	ds_read_b128 v[186:189], v174 offset:3072
	ds_read_b128 v[190:193], v175
	ds_read_b128 v[194:197], v175 offset:1024
	ds_read_b128 v[198:201], v175 offset:2048
	ds_read_b128 v[202:205], v175 offset:3072
	s_add_u32 s28, s26, 0xfff80080
	s_addc_u32 s29, s27, -1
	s_cmp_eq_u32 s54, 28
	s_cselect_b32 s31, s7, s29
	s_cselect_b32 s30, s19, s28
	s_cselect_b32 s29, s17, s53
	s_cselect_b32 s28, s25, s52
	s_add_i32 m0, s39, 0xc000
	ds_read_b128 v[206:209], v176
	ds_read_b128 v[210:213], v176 offset:1024
	ds_read_b128 v[214:217], v176 offset:2048
	ds_read_b128 v[218:221], v176 offset:3072
	ds_read_b128 v[222:225], v176 offset:4096
	ds_read_b128 v[226:229], v176 offset:5120
	ds_read_b128 v[230:233], v176 offset:6144
	ds_read_b128 v[234:237], v176 offset:7168
	global_load_lds_dwordx4 v136, s[26:27]
	s_add_i32 m0, s39, 0xe000
	s_nop 0
	global_load_lds_dwordx4 v138, s[26:27]
	s_waitcnt vmcnt(8)
	s_waitcnt lgkmcnt(0)
	s_barrier
	s_setprio 1
	s_waitcnt lgkmcnt(0)
	v_mfma_f32_16x16x32_bf16 v[124:127], v[144:147], v[206:209], v[124:127]
	v_mfma_f32_16x16x32_bf16 v[120:123], v[182:185], v[206:209], v[120:123]
	v_mfma_f32_16x16x32_bf16 v[108:111], v[144:147], v[214:217], v[108:111]
	v_mfma_f32_16x16x32_bf16 v[104:107], v[182:185], v[214:217], v[104:107]
	v_mfma_f32_16x16x32_bf16 v[92:95], v[144:147], v[222:225], v[92:95]
	v_mfma_f32_16x16x32_bf16 v[88:91], v[182:185], v[222:225], v[88:91]
	v_mfma_f32_16x16x32_bf16 v[76:79], v[144:147], v[230:233], v[76:79]
	v_mfma_f32_16x16x32_bf16 v[72:75], v[182:185], v[230:233], v[72:75]
	v_mfma_f32_16x16x32_bf16 v[124:127], v[178:181], v[210:213], v[124:127]
	v_mfma_f32_16x16x32_bf16 v[120:123], v[186:189], v[210:213], v[120:123]
	v_mfma_f32_16x16x32_bf16 v[108:111], v[178:181], v[218:221], v[108:111]
	v_mfma_f32_16x16x32_bf16 v[104:107], v[186:189], v[218:221], v[104:107]
	v_mfma_f32_16x16x32_bf16 v[92:95], v[178:181], v[226:229], v[92:95]
	v_mfma_f32_16x16x32_bf16 v[88:91], v[186:189], v[226:229], v[88:91]
	v_mfma_f32_16x16x32_bf16 v[76:79], v[178:181], v[234:237], v[76:79]
	v_mfma_f32_16x16x32_bf16 v[72:75], v[186:189], v[234:237], v[72:75]
	s_setprio 0
	s_setprio 1
	v_mfma_f32_16x16x32_bf16 v[116:119], v[190:193], v[206:209], v[116:119]
	v_mfma_f32_16x16x32_bf16 v[112:115], v[198:201], v[206:209], v[112:115]
	v_mfma_f32_16x16x32_bf16 v[100:103], v[190:193], v[214:217], v[100:103]
	v_mfma_f32_16x16x32_bf16 v[96:99], v[198:201], v[214:217], v[96:99]
	v_mfma_f32_16x16x32_bf16 v[84:87], v[190:193], v[222:225], v[84:87]
	v_mfma_f32_16x16x32_bf16 v[80:83], v[198:201], v[222:225], v[80:83]
	v_mfma_f32_16x16x32_bf16 v[68:71], v[190:193], v[230:233], v[68:71]
	v_mfma_f32_16x16x32_bf16 v[64:67], v[198:201], v[230:233], v[64:67]
	v_mfma_f32_16x16x32_bf16 v[116:119], v[194:197], v[210:213], v[116:119]
	v_mfma_f32_16x16x32_bf16 v[112:115], v[202:205], v[210:213], v[112:115]
	v_mfma_f32_16x16x32_bf16 v[100:103], v[194:197], v[218:221], v[100:103]
	v_mfma_f32_16x16x32_bf16 v[96:99], v[202:205], v[218:221], v[96:99]
	v_mfma_f32_16x16x32_bf16 v[84:87], v[194:197], v[226:229], v[84:87]
	v_mfma_f32_16x16x32_bf16 v[80:83], v[202:205], v[226:229], v[80:83]
	v_mfma_f32_16x16x32_bf16 v[68:71], v[194:197], v[234:237], v[68:71]
	v_mfma_f32_16x16x32_bf16 v[64:67], v[202:205], v[234:237], v[64:67]
	s_setprio 0
	s_barrier
	s_add_i32 s55, s50, s38
	s_add_u32 s70, s28, 0x80
	s_addc_u32 s71, s29, 0
	s_mov_b32 m0, s55
	ds_read_b128 v[206:209], v176 offset:16384
	ds_read_b128 v[210:213], v176 offset:17408
	ds_read_b128 v[214:217], v176 offset:18432
	ds_read_b128 v[218:221], v176 offset:19456
	ds_read_b128 v[222:225], v176 offset:20480
	ds_read_b128 v[226:229], v176 offset:21504
	ds_read_b128 v[230:233], v176 offset:22528
	ds_read_b128 v[234:237], v176 offset:23552
	global_load_lds_dwordx4 v130, s[28:29]
	s_add_i32 m0, s55, 0x2000
	s_add_u32 s56, s28, 0x80000
	s_addc_u32 s57, s29, 0
	s_add_i32 s55, s51, s38
	global_load_lds_dwordx4 v134, s[28:29]
	s_mov_b32 m0, s55
	s_nop 0
	global_load_lds_dwordx4 v130, s[56:57]
	s_add_i32 m0, s55, 0x2000
	s_nop 0
	global_load_lds_dwordx4 v134, s[56:57]
	s_add_u32 s74, s30, 0x80
	s_addc_u32 s75, s31, 0
	s_mov_b32 m0, s39
	s_nop 0
	global_load_lds_dwordx4 v128, s[30:31]
	s_mov_b32 m0, s40
	s_nop 0
	global_load_lds_dwordx4 v132, s[30:31]
	s_waitcnt vmcnt(8)
	s_waitcnt lgkmcnt(0)
	s_barrier
	s_setprio 1
	s_waitcnt lgkmcnt(0)
	v_mfma_f32_16x16x32_bf16 v[60:63], v[144:147], v[206:209], v[60:63]
	v_mfma_f32_16x16x32_bf16 v[56:59], v[182:185], v[206:209], v[56:59]
	v_mfma_f32_16x16x32_bf16 v[44:47], v[144:147], v[214:217], v[44:47]
	v_mfma_f32_16x16x32_bf16 v[40:43], v[182:185], v[214:217], v[40:43]
	v_mfma_f32_16x16x32_bf16 v[28:31], v[144:147], v[222:225], v[28:31]
	v_mfma_f32_16x16x32_bf16 v[24:27], v[182:185], v[222:225], v[24:27]
	v_mfma_f32_16x16x32_bf16 v[12:15], v[144:147], v[230:233], v[12:15]
	v_mfma_f32_16x16x32_bf16 v[8:11], v[182:185], v[230:233], v[8:11]
	v_mfma_f32_16x16x32_bf16 v[60:63], v[178:181], v[210:213], v[60:63]
	v_mfma_f32_16x16x32_bf16 v[56:59], v[186:189], v[210:213], v[56:59]
	v_mfma_f32_16x16x32_bf16 v[44:47], v[178:181], v[218:221], v[44:47]
	v_mfma_f32_16x16x32_bf16 v[40:43], v[186:189], v[218:221], v[40:43]
	v_mfma_f32_16x16x32_bf16 v[28:31], v[178:181], v[226:229], v[28:31]
	v_mfma_f32_16x16x32_bf16 v[24:27], v[186:189], v[226:229], v[24:27]
	v_mfma_f32_16x16x32_bf16 v[12:15], v[178:181], v[234:237], v[12:15]
	v_mfma_f32_16x16x32_bf16 v[8:11], v[186:189], v[234:237], v[8:11]
	s_setprio 0
	s_setprio 1
	v_mfma_f32_16x16x32_bf16 v[52:55], v[190:193], v[206:209], v[52:55]
	v_mfma_f32_16x16x32_bf16 v[48:51], v[198:201], v[206:209], v[48:51]
	v_mfma_f32_16x16x32_bf16 v[36:39], v[190:193], v[214:217], v[36:39]
	v_mfma_f32_16x16x32_bf16 v[32:35], v[198:201], v[214:217], v[32:35]
	v_mfma_f32_16x16x32_bf16 v[20:23], v[190:193], v[222:225], v[20:23]
	v_mfma_f32_16x16x32_bf16 v[16:19], v[198:201], v[222:225], v[16:19]
	v_mfma_f32_16x16x32_bf16 v[4:7], v[190:193], v[230:233], v[4:7]
	v_mfma_f32_16x16x32_bf16 v[0:3], v[198:201], v[230:233], v[0:3]
	v_mfma_f32_16x16x32_bf16 v[52:55], v[194:197], v[210:213], v[52:55]
	v_mfma_f32_16x16x32_bf16 v[48:51], v[202:205], v[210:213], v[48:51]
	v_mfma_f32_16x16x32_bf16 v[36:39], v[194:197], v[218:221], v[36:39]
	v_mfma_f32_16x16x32_bf16 v[32:35], v[202:205], v[218:221], v[32:35]
	v_mfma_f32_16x16x32_bf16 v[20:23], v[194:197], v[226:229], v[20:23]
	v_mfma_f32_16x16x32_bf16 v[16:19], v[202:205], v[226:229], v[16:19]
	v_mfma_f32_16x16x32_bf16 v[4:7], v[194:197], v[234:237], v[4:7]
	v_mfma_f32_16x16x32_bf16 v[0:3], v[202:205], v[234:237], v[0:3]
	s_setprio 0
	s_barrier
	s_add_i32 s55, 0, 0x18000
	v_add_u32_e32 v177, s55, v149
	s_add_i32 s56, 0, 0x1c000
	ds_read_b128 v[144:147], v177
	ds_read_b128 v[178:181], v177 offset:1024
	ds_read_b128 v[182:185], v177 offset:2048
	ds_read_b128 v[186:189], v177 offset:3072
	v_add_u32_e32 v177, s56, v149
	ds_read_b128 v[190:193], v177
	ds_read_b128 v[194:197], v177 offset:1024
	ds_read_b128 v[198:201], v177 offset:2048
	ds_read_b128 v[202:205], v177 offset:3072
	s_add_u32 s30, s30, 0x80000
	s_addc_u32 s31, s31, 0
	s_mov_b32 m0, s41
	ds_read_b128 v[206:209], v176 offset:32768
	ds_read_b128 v[210:213], v176 offset:33792
	ds_read_b128 v[214:217], v176 offset:34816
	ds_read_b128 v[218:221], v176 offset:35840
	ds_read_b128 v[222:225], v176 offset:36864
	ds_read_b128 v[226:229], v176 offset:37888
	ds_read_b128 v[230:233], v176 offset:38912
	ds_read_b128 v[234:237], v176 offset:39936
	global_load_lds_dwordx4 v128, s[30:31]
	s_mov_b32 m0, s42
	s_nop 0
	global_load_lds_dwordx4 v132, s[30:31]
	s_waitcnt vmcnt(8)
	s_waitcnt lgkmcnt(0)
	s_barrier
	s_setprio 1
	s_waitcnt lgkmcnt(0)
	v_mfma_f32_16x16x32_bf16 v[124:127], v[144:147], v[206:209], v[124:127]
	v_mfma_f32_16x16x32_bf16 v[120:123], v[182:185], v[206:209], v[120:123]
	v_mfma_f32_16x16x32_bf16 v[108:111], v[144:147], v[214:217], v[108:111]
	v_mfma_f32_16x16x32_bf16 v[104:107], v[182:185], v[214:217], v[104:107]
	v_mfma_f32_16x16x32_bf16 v[92:95], v[144:147], v[222:225], v[92:95]
	v_mfma_f32_16x16x32_bf16 v[88:91], v[182:185], v[222:225], v[88:91]
	v_mfma_f32_16x16x32_bf16 v[76:79], v[144:147], v[230:233], v[76:79]
	v_mfma_f32_16x16x32_bf16 v[72:75], v[182:185], v[230:233], v[72:75]
	v_mfma_f32_16x16x32_bf16 v[124:127], v[178:181], v[210:213], v[124:127]
	v_mfma_f32_16x16x32_bf16 v[120:123], v[186:189], v[210:213], v[120:123]
	v_mfma_f32_16x16x32_bf16 v[108:111], v[178:181], v[218:221], v[108:111]
	v_mfma_f32_16x16x32_bf16 v[104:107], v[186:189], v[218:221], v[104:107]
	v_mfma_f32_16x16x32_bf16 v[92:95], v[178:181], v[226:229], v[92:95]
	v_mfma_f32_16x16x32_bf16 v[88:91], v[186:189], v[226:229], v[88:91]
	v_mfma_f32_16x16x32_bf16 v[76:79], v[178:181], v[234:237], v[76:79]
	v_mfma_f32_16x16x32_bf16 v[72:75], v[186:189], v[234:237], v[72:75]
	s_setprio 0
	s_setprio 1
	v_mfma_f32_16x16x32_bf16 v[116:119], v[190:193], v[206:209], v[116:119]
	v_mfma_f32_16x16x32_bf16 v[112:115], v[198:201], v[206:209], v[112:115]
	v_mfma_f32_16x16x32_bf16 v[100:103], v[190:193], v[214:217], v[100:103]
	v_mfma_f32_16x16x32_bf16 v[96:99], v[198:201], v[214:217], v[96:99]
	v_mfma_f32_16x16x32_bf16 v[84:87], v[190:193], v[222:225], v[84:87]
	v_mfma_f32_16x16x32_bf16 v[80:83], v[198:201], v[222:225], v[80:83]
	v_mfma_f32_16x16x32_bf16 v[68:71], v[190:193], v[230:233], v[68:71]
	v_mfma_f32_16x16x32_bf16 v[64:67], v[198:201], v[230:233], v[64:67]
	v_mfma_f32_16x16x32_bf16 v[116:119], v[194:197], v[210:213], v[116:119]
	v_mfma_f32_16x16x32_bf16 v[112:115], v[202:205], v[210:213], v[112:115]
	v_mfma_f32_16x16x32_bf16 v[100:103], v[194:197], v[218:221], v[100:103]
	v_mfma_f32_16x16x32_bf16 v[96:99], v[202:205], v[218:221], v[96:99]
	v_mfma_f32_16x16x32_bf16 v[84:87], v[194:197], v[226:229], v[84:87]
	v_mfma_f32_16x16x32_bf16 v[80:83], v[202:205], v[226:229], v[80:83]
	v_mfma_f32_16x16x32_bf16 v[68:71], v[194:197], v[234:237], v[68:71]
	v_mfma_f32_16x16x32_bf16 v[64:67], v[202:205], v[234:237], v[64:67]
	s_setprio 0
	s_barrier
	s_add_i32 s30, s55, s38
	s_mov_b32 m0, s30
	ds_read_b128 v[206:209], v176 offset:49152
	ds_read_b128 v[210:213], v176 offset:50176
	ds_read_b128 v[214:217], v176 offset:51200
	ds_read_b128 v[218:221], v176 offset:52224
	ds_read_b128 v[222:225], v176 offset:53248
	ds_read_b128 v[226:229], v176 offset:54272
	ds_read_b128 v[230:233], v176 offset:55296
	ds_read_b128 v[234:237], v176 offset:56320
	global_load_lds_dwordx4 v130, s[70:71]
	s_add_i32 m0, s30, 0x2000
	s_add_u32 s28, s28, 0x80080
	s_addc_u32 s29, s29, 0
	s_add_i32 s30, s56, s38
	global_load_lds_dwordx4 v134, s[70:71]
	s_mov_b32 m0, s30
	s_nop 0
	global_load_lds_dwordx4 v130, s[28:29]
	s_add_i32 m0, s30, 0x2000
	s_nop 0
	global_load_lds_dwordx4 v134, s[28:29]
	s_mov_b32 m0, s46
	s_nop 0
	global_load_lds_dwordx4 v128, s[74:75]
	s_mov_b32 m0, s47
	s_nop 0
	global_load_lds_dwordx4 v132, s[74:75]
	s_waitcnt vmcnt(8)
	s_waitcnt lgkmcnt(0)
	s_barrier
	s_setprio 1
	s_waitcnt lgkmcnt(0)
	v_mfma_f32_16x16x32_bf16 v[60:63], v[144:147], v[206:209], v[60:63]
	v_mfma_f32_16x16x32_bf16 v[56:59], v[182:185], v[206:209], v[56:59]
	v_mfma_f32_16x16x32_bf16 v[44:47], v[144:147], v[214:217], v[44:47]
	v_mfma_f32_16x16x32_bf16 v[40:43], v[182:185], v[214:217], v[40:43]
	v_mfma_f32_16x16x32_bf16 v[28:31], v[144:147], v[222:225], v[28:31]
	v_mfma_f32_16x16x32_bf16 v[24:27], v[182:185], v[222:225], v[24:27]
	v_mfma_f32_16x16x32_bf16 v[12:15], v[144:147], v[230:233], v[12:15]
	v_mfma_f32_16x16x32_bf16 v[8:11], v[182:185], v[230:233], v[8:11]
	v_mfma_f32_16x16x32_bf16 v[60:63], v[178:181], v[210:213], v[60:63]
	v_mfma_f32_16x16x32_bf16 v[56:59], v[186:189], v[210:213], v[56:59]
	v_mfma_f32_16x16x32_bf16 v[44:47], v[178:181], v[218:221], v[44:47]
	v_mfma_f32_16x16x32_bf16 v[40:43], v[186:189], v[218:221], v[40:43]
	v_mfma_f32_16x16x32_bf16 v[28:31], v[178:181], v[226:229], v[28:31]
	v_mfma_f32_16x16x32_bf16 v[24:27], v[186:189], v[226:229], v[24:27]
	v_mfma_f32_16x16x32_bf16 v[12:15], v[178:181], v[234:237], v[12:15]
	v_mfma_f32_16x16x32_bf16 v[8:11], v[186:189], v[234:237], v[8:11]
	s_setprio 0
	s_setprio 1
	v_mfma_f32_16x16x32_bf16 v[52:55], v[190:193], v[206:209], v[52:55]
	v_mfma_f32_16x16x32_bf16 v[48:51], v[198:201], v[206:209], v[48:51]
	v_mfma_f32_16x16x32_bf16 v[36:39], v[190:193], v[214:217], v[36:39]
	v_mfma_f32_16x16x32_bf16 v[32:35], v[198:201], v[214:217], v[32:35]
	v_mfma_f32_16x16x32_bf16 v[20:23], v[190:193], v[222:225], v[20:23]
	v_mfma_f32_16x16x32_bf16 v[16:19], v[198:201], v[222:225], v[16:19]
	v_mfma_f32_16x16x32_bf16 v[4:7], v[190:193], v[230:233], v[4:7]
	v_mfma_f32_16x16x32_bf16 v[0:3], v[198:201], v[230:233], v[0:3]
	v_mfma_f32_16x16x32_bf16 v[52:55], v[194:197], v[210:213], v[52:55]
	v_mfma_f32_16x16x32_bf16 v[48:51], v[202:205], v[210:213], v[48:51]
	v_mfma_f32_16x16x32_bf16 v[36:39], v[194:197], v[218:221], v[36:39]
	v_mfma_f32_16x16x32_bf16 v[32:35], v[202:205], v[218:221], v[32:35]
	v_mfma_f32_16x16x32_bf16 v[20:23], v[194:197], v[226:229], v[20:23]
	v_mfma_f32_16x16x32_bf16 v[16:19], v[202:205], v[226:229], v[16:19]
	v_mfma_f32_16x16x32_bf16 v[4:7], v[194:197], v[234:237], v[4:7]
	v_mfma_f32_16x16x32_bf16 v[0:3], v[202:205], v[234:237], v[0:3]
	s_setprio 0
	s_barrier
	s_add_i32 s54, s54, 2
	s_add_u32 s26, s26, 0x100
	s_addc_u32 s27, s27, 0
	s_add_u32 s52, s52, 0x100
	s_addc_u32 s53, s53, 0
	s_cmp_gt_u32 s54, 29
	s_cbranch_scc0 .LBB0_884

.LBB0_989:
	s_nop 0
	s_cmp_gt_i32 s92, 4
	s_cselect_b64 s[8:9], -1, 0
	s_cmp_lt_i32 s92, 5
	s_cselect_b64 s[0:1], -1, 0
	s_cmp_gt_i32 s93, 4
	s_cselect_b64 s[2:3], -1, 0
	s_and_b64 s[0:1], s[0:1], s[2:3]
	s_andn2_b64 vcc, exec, s[0:1]
	s_cbranch_vccnz .LBB0_1185
	v_readlane_b32 s0, v254, 16
	v_readlane_b32 s6, v254, 22
	v_readlane_b32 s7, v254, 23
	s_add_u32 s33, s6, 0x6000000
	s_addc_u32 s34, s7, 0
	s_add_u32 s14, s6, 0x500000
	s_addc_u32 s15, s7, 0
	v_mbcnt_lo_u32_b32 v24, -1, 0
	v_mbcnt_hi_u32_b32 v24, -1, v24
	s_cmpk_lt_i32 s69, 0x100
	v_and_b32_e32 v25, 15, v24
	v_readlane_b32 s1, v254, 17
	v_readlane_b32 s2, v254, 18
	v_readlane_b32 s3, v254, 19
	v_readlane_b32 s4, v254, 20
	v_readlane_b32 s5, v254, 21
	s_cbranch_scc1 .LBB0_992
	v_and_b32_e32 v8, 15, v24
	s_cbranch_execz .LBB0_993
	s_branch .LBB0_1002

.LBB0_1022:
	v_add_u32_e32 v126, s48, v160
	ds_read_b128 v[154:157], v126
	ds_read_b128 v[188:191], v126 offset:1024
	ds_read_b128 v[192:195], v126 offset:2048
	ds_read_b128 v[196:199], v126 offset:3072
	v_add_u32_e32 v126, s49, v160
	s_add_u32 s28, s4, s26
	ds_read_b128 v[200:203], v126
	ds_read_b128 v[204:207], v126 offset:1024
	ds_read_b128 v[208:211], v126 offset:2048
	ds_read_b128 v[212:215], v126 offset:3072
	s_addc_u32 s29, s5, s27
	s_mov_b64 s[70:71], s[28:29]
	s_add_u32 s28, s28, 0x100
	s_addc_u32 s29, s29, 0
	s_add_u32 s56, s23, s26
	s_addc_u32 s57, s54, s27
	s_cmpk_eq_i32 s26, 0xf00
	s_cselect_b32 s31, s17, s29
	s_cselect_b32 s30, s52, s28
	s_cselect_b32 s29, s15, s57
	s_cselect_b32 s28, s53, s56
	s_add_i32 m0, s25, 0xc000
	ds_read_b128 v[216:219], v178
	ds_read_b128 v[220:223], v178 offset:1024
	ds_read_b128 v[224:227], v178 offset:2048
	ds_read_b128 v[228:231], v178 offset:3072
	ds_read_b128 v[232:235], v178 offset:4096
	ds_read_b128 v[236:239], v178 offset:5120
	ds_read_b128 v[240:243], v178 offset:6144
	ds_read_b128 v[244:247], v178 offset:7168
	global_load_lds_dwordx4 v150, s[70:71]
	s_add_i32 m0, s25, 0xe000
	s_nop 0
	global_load_lds_dwordx4 v152, s[70:71]
	s_waitcnt vmcnt(8)
	s_waitcnt lgkmcnt(0)
	s_barrier
	s_setprio 1
	s_waitcnt lgkmcnt(0)
	v_mfma_f32_16x16x32_bf16 v[116:119], v[154:157], v[216:219], v[116:119]
	v_mfma_f32_16x16x32_bf16 v[108:111], v[192:195], v[216:219], v[108:111]
	v_mfma_f32_16x16x32_bf16 v[112:115], v[154:157], v[224:227], v[112:115]
	v_mfma_f32_16x16x32_bf16 v[92:95], v[192:195], v[224:227], v[92:95]
	v_mfma_f32_16x16x32_bf16 v[96:99], v[154:157], v[232:235], v[96:99]
	v_mfma_f32_16x16x32_bf16 v[76:79], v[192:195], v[232:235], v[76:79]
	v_mfma_f32_16x16x32_bf16 v[80:83], v[154:157], v[240:243], v[80:83]
	v_mfma_f32_16x16x32_bf16 v[64:67], v[192:195], v[240:243], v[64:67]
	v_mfma_f32_16x16x32_bf16 v[116:119], v[188:191], v[220:223], v[116:119]
	v_mfma_f32_16x16x32_bf16 v[108:111], v[196:199], v[220:223], v[108:111]
	v_mfma_f32_16x16x32_bf16 v[112:115], v[188:191], v[228:231], v[112:115]
	v_mfma_f32_16x16x32_bf16 v[92:95], v[196:199], v[228:231], v[92:95]
	v_mfma_f32_16x16x32_bf16 v[96:99], v[188:191], v[236:239], v[96:99]
	v_mfma_f32_16x16x32_bf16 v[76:79], v[196:199], v[236:239], v[76:79]
	v_mfma_f32_16x16x32_bf16 v[80:83], v[188:191], v[244:247], v[80:83]
	v_mfma_f32_16x16x32_bf16 v[64:67], v[196:199], v[244:247], v[64:67]
	s_setprio 0
	s_setprio 1
	v_mfma_f32_16x16x32_bf16 v[104:107], v[200:203], v[216:219], v[104:107]
	v_mfma_f32_16x16x32_bf16 v[100:103], v[208:211], v[216:219], v[100:103]
	v_mfma_f32_16x16x32_bf16 v[88:91], v[200:203], v[224:227], v[88:91]
	v_mfma_f32_16x16x32_bf16 v[84:87], v[208:211], v[224:227], v[84:87]
	v_mfma_f32_16x16x32_bf16 v[72:75], v[200:203], v[232:235], v[72:75]
	v_mfma_f32_16x16x32_bf16 v[68:71], v[208:211], v[232:235], v[68:71]
	v_mfma_f32_16x16x32_bf16 v[60:63], v[200:203], v[240:243], v[60:63]
	v_mfma_f32_16x16x32_bf16 v[56:59], v[208:211], v[240:243], v[56:59]
	v_mfma_f32_16x16x32_bf16 v[104:107], v[204:207], v[220:223], v[104:107]
	v_mfma_f32_16x16x32_bf16 v[100:103], v[212:215], v[220:223], v[100:103]
	v_mfma_f32_16x16x32_bf16 v[88:91], v[204:207], v[228:231], v[88:91]
	v_mfma_f32_16x16x32_bf16 v[84:87], v[212:215], v[228:231], v[84:87]
	v_mfma_f32_16x16x32_bf16 v[72:75], v[204:207], v[236:239], v[72:75]
	v_mfma_f32_16x16x32_bf16 v[68:71], v[212:215], v[236:239], v[68:71]
	v_mfma_f32_16x16x32_bf16 v[60:63], v[204:207], v[244:247], v[60:63]
	v_mfma_f32_16x16x32_bf16 v[56:59], v[212:215], v[244:247], v[56:59]
	s_setprio 0
	s_barrier
	s_add_i32 s56, s48, s36
	s_add_u32 s74, s28, 0x80
	s_addc_u32 s75, s29, 0
	s_mov_b32 m0, s56
	ds_read_b128 v[216:219], v178 offset:16384
	ds_read_b128 v[220:223], v178 offset:17408
	ds_read_b128 v[224:227], v178 offset:18432
	ds_read_b128 v[228:231], v178 offset:19456
	ds_read_b128 v[232:235], v178 offset:20480
	ds_read_b128 v[236:239], v178 offset:21504
	ds_read_b128 v[240:243], v178 offset:22528
	ds_read_b128 v[244:247], v178 offset:23552
	global_load_lds_dwordx4 v138, s[28:29]
	s_add_i32 m0, s56, 0x2000
	s_add_u32 s56, s28, 0x80000
	s_addc_u32 s57, s29, 0
	s_add_i32 s58, s49, s36
	global_load_lds_dwordx4 v142, s[28:29]
	s_mov_b32 m0, s58
	s_add_u32 s78, s30, 0x80
	s_addc_u32 s79, s31, 0
	global_load_lds_dwordx4 v138, s[56:57]
	s_add_i32 m0, s58, 0x2000
	s_nop 0
	global_load_lds_dwordx4 v142, s[56:57]
	s_mov_b32 m0, s25
	s_nop 0
	global_load_lds_dwordx4 v136, s[30:31]
	s_mov_b32 m0, s39
	s_nop 0
	global_load_lds_dwordx4 v140, s[30:31]
	s_waitcnt vmcnt(8)
	s_waitcnt lgkmcnt(0)
	s_barrier
	s_setprio 1
	s_waitcnt lgkmcnt(0)
	v_mfma_f32_16x16x32_bf16 v[52:55], v[154:157], v[216:219], v[52:55]
	v_mfma_f32_16x16x32_bf16 v[44:47], v[192:195], v[216:219], v[44:47]
	v_mfma_f32_16x16x32_bf16 v[48:51], v[154:157], v[224:227], v[48:51]
	v_mfma_f32_16x16x32_bf16 v[28:31], v[192:195], v[224:227], v[28:31]
	v_mfma_f32_16x16x32_bf16 v[32:35], v[154:157], v[232:235], v[32:35]
	v_mfma_f32_16x16x32_bf16 v[16:19], v[192:195], v[232:235], v[16:19]
	v_mfma_f32_16x16x32_bf16 v[132:135], v[154:157], v[240:243], v[132:135]
	v_mfma_f32_16x16x32_bf16 v[126:129], v[192:195], v[240:243], v[128:131]
	v_mfma_f32_16x16x32_bf16 v[52:55], v[188:191], v[220:223], v[52:55]
	v_mfma_f32_16x16x32_bf16 v[44:47], v[196:199], v[220:223], v[44:47]
	v_mfma_f32_16x16x32_bf16 v[48:51], v[188:191], v[228:231], v[48:51]
	v_mfma_f32_16x16x32_bf16 v[28:31], v[196:199], v[228:231], v[28:31]
	v_mfma_f32_16x16x32_bf16 v[32:35], v[188:191], v[236:239], v[32:35]
	v_mfma_f32_16x16x32_bf16 v[16:19], v[196:199], v[236:239], v[16:19]
	v_mfma_f32_16x16x32_bf16 v[132:135], v[188:191], v[244:247], v[132:135]
	v_mfma_f32_16x16x32_bf16 v[126:129], v[196:199], v[244:247], v[126:129]
	s_setprio 0
	s_setprio 1
	v_mfma_f32_16x16x32_bf16 v[40:43], v[200:203], v[216:219], v[40:43]
	v_mfma_f32_16x16x32_bf16 v[36:39], v[208:211], v[216:219], v[36:39]
	v_mfma_f32_16x16x32_bf16 v[24:27], v[200:203], v[224:227], v[24:27]
	v_mfma_f32_16x16x32_bf16 v[20:23], v[208:211], v[224:227], v[20:23]
	v_mfma_f32_16x16x32_bf16 v[12:15], v[200:203], v[232:235], v[12:15]
	v_mfma_f32_16x16x32_bf16 v[8:11], v[208:211], v[232:235], v[8:11]
	v_mfma_f32_16x16x32_bf16 v[0:3], v[200:203], v[240:243], v[0:3]
	v_mfma_f32_16x16x32_bf16 v[4:7], v[208:211], v[240:243], v[4:7]
	v_mfma_f32_16x16x32_bf16 v[40:43], v[204:207], v[220:223], v[40:43]
	v_mfma_f32_16x16x32_bf16 v[36:39], v[212:215], v[220:223], v[36:39]
	v_mfma_f32_16x16x32_bf16 v[24:27], v[204:207], v[228:231], v[24:27]
	v_mfma_f32_16x16x32_bf16 v[20:23], v[212:215], v[228:231], v[20:23]
	v_mfma_f32_16x16x32_bf16 v[12:15], v[204:207], v[236:239], v[12:15]
	v_mfma_f32_16x16x32_bf16 v[8:11], v[212:215], v[236:239], v[8:11]
	v_mfma_f32_16x16x32_bf16 v[0:3], v[204:207], v[244:247], v[0:3]
	v_mfma_f32_16x16x32_bf16 v[4:7], v[212:215], v[244:247], v[4:7]
	s_setprio 0
	s_barrier
	s_add_i32 s56, 0, 0x18000
	v_add_u32_e32 v130, s56, v160
	s_add_i32 s57, 0, 0x1c000
	ds_read_b128 v[154:157], v130
	ds_read_b128 v[188:191], v130 offset:1024
	ds_read_b128 v[192:195], v130 offset:2048
	ds_read_b128 v[196:199], v130 offset:3072
	v_add_u32_e32 v130, s57, v160
	ds_read_b128 v[200:203], v130
	ds_read_b128 v[204:207], v130 offset:1024
	ds_read_b128 v[208:211], v130 offset:2048
	ds_read_b128 v[212:215], v130 offset:3072
	s_add_u32 s30, s30, 0x80000
	s_addc_u32 s31, s31, 0
	s_mov_b32 m0, s40
	ds_read_b128 v[216:219], v178 offset:32768
	ds_read_b128 v[220:223], v178 offset:33792
	ds_read_b128 v[224:227], v178 offset:34816
	ds_read_b128 v[228:231], v178 offset:35840
	ds_read_b128 v[232:235], v178 offset:36864
	ds_read_b128 v[236:239], v178 offset:37888
	ds_read_b128 v[240:243], v178 offset:38912
	ds_read_b128 v[244:247], v178 offset:39936
	global_load_lds_dwordx4 v136, s[30:31]
	s_mov_b32 m0, s41
	s_nop 0
	global_load_lds_dwordx4 v140, s[30:31]
	s_waitcnt vmcnt(8)
	s_waitcnt lgkmcnt(0)
	s_barrier
	s_setprio 1
	s_waitcnt lgkmcnt(0)
	v_mfma_f32_16x16x32_bf16 v[116:119], v[154:157], v[216:219], v[116:119]
	v_mfma_f32_16x16x32_bf16 v[108:111], v[192:195], v[216:219], v[108:111]
	v_mfma_f32_16x16x32_bf16 v[112:115], v[154:157], v[224:227], v[112:115]
	v_mfma_f32_16x16x32_bf16 v[92:95], v[192:195], v[224:227], v[92:95]
	v_mfma_f32_16x16x32_bf16 v[96:99], v[154:157], v[232:235], v[96:99]
	v_mfma_f32_16x16x32_bf16 v[76:79], v[192:195], v[232:235], v[76:79]
	v_mfma_f32_16x16x32_bf16 v[80:83], v[154:157], v[240:243], v[80:83]
	v_mfma_f32_16x16x32_bf16 v[64:67], v[192:195], v[240:243], v[64:67]
	v_mfma_f32_16x16x32_bf16 v[116:119], v[188:191], v[220:223], v[116:119]
	v_mfma_f32_16x16x32_bf16 v[108:111], v[196:199], v[220:223], v[108:111]
	v_mfma_f32_16x16x32_bf16 v[112:115], v[188:191], v[228:231], v[112:115]
	v_mfma_f32_16x16x32_bf16 v[92:95], v[196:199], v[228:231], v[92:95]
	v_mfma_f32_16x16x32_bf16 v[96:99], v[188:191], v[236:239], v[96:99]
	v_mfma_f32_16x16x32_bf16 v[76:79], v[196:199], v[236:239], v[76:79]
	v_mfma_f32_16x16x32_bf16 v[80:83], v[188:191], v[244:247], v[80:83]
	v_mfma_f32_16x16x32_bf16 v[64:67], v[196:199], v[244:247], v[64:67]
	s_setprio 0
	s_setprio 1
	v_mfma_f32_16x16x32_bf16 v[104:107], v[200:203], v[216:219], v[104:107]
	v_mfma_f32_16x16x32_bf16 v[100:103], v[208:211], v[216:219], v[100:103]
	v_mfma_f32_16x16x32_bf16 v[88:91], v[200:203], v[224:227], v[88:91]
	v_mfma_f32_16x16x32_bf16 v[84:87], v[208:211], v[224:227], v[84:87]
	v_mfma_f32_16x16x32_bf16 v[72:75], v[200:203], v[232:235], v[72:75]
	v_mfma_f32_16x16x32_bf16 v[68:71], v[208:211], v[232:235], v[68:71]
	v_mfma_f32_16x16x32_bf16 v[60:63], v[200:203], v[240:243], v[60:63]
	v_mfma_f32_16x16x32_bf16 v[56:59], v[208:211], v[240:243], v[56:59]
	v_mfma_f32_16x16x32_bf16 v[104:107], v[204:207], v[220:223], v[104:107]
	v_mfma_f32_16x16x32_bf16 v[100:103], v[212:215], v[220:223], v[100:103]
	v_mfma_f32_16x16x32_bf16 v[88:91], v[204:207], v[228:231], v[88:91]
	v_mfma_f32_16x16x32_bf16 v[84:87], v[212:215], v[228:231], v[84:87]
	v_mfma_f32_16x16x32_bf16 v[72:75], v[204:207], v[236:239], v[72:75]
	v_mfma_f32_16x16x32_bf16 v[68:71], v[212:215], v[236:239], v[68:71]
	v_mfma_f32_16x16x32_bf16 v[60:63], v[204:207], v[244:247], v[60:63]
	v_mfma_f32_16x16x32_bf16 v[56:59], v[212:215], v[244:247], v[56:59]
	s_setprio 0
	s_barrier
	s_add_i32 s30, s56, s36
	s_mov_b32 m0, s30
	ds_read_b128 v[216:219], v178 offset:49152
	ds_read_b128 v[220:223], v178 offset:50176
	ds_read_b128 v[224:227], v178 offset:51200
	ds_read_b128 v[228:231], v178 offset:52224
	ds_read_b128 v[232:235], v178 offset:53248
	ds_read_b128 v[236:239], v178 offset:54272
	ds_read_b128 v[240:243], v178 offset:55296
	ds_read_b128 v[244:247], v178 offset:56320
	global_load_lds_dwordx4 v138, s[74:75]
	s_add_i32 m0, s30, 0x2000
	s_add_u32 s28, s28, 0x80080
	s_addc_u32 s29, s29, 0
	s_add_i32 s30, s57, s36
	global_load_lds_dwordx4 v142, s[74:75]
	s_mov_b32 m0, s30
	s_nop 0
	global_load_lds_dwordx4 v138, s[28:29]
	s_add_i32 m0, s30, 0x2000
	s_nop 0
	global_load_lds_dwordx4 v142, s[28:29]
	s_mov_b32 m0, s44
	s_nop 0
	global_load_lds_dwordx4 v136, s[78:79]
	s_mov_b32 m0, s45
	s_nop 0
	global_load_lds_dwordx4 v140, s[78:79]
	s_waitcnt vmcnt(8)
	s_waitcnt lgkmcnt(0)
	s_barrier
	s_setprio 1
	s_waitcnt lgkmcnt(0)
	v_mfma_f32_16x16x32_bf16 v[52:55], v[154:157], v[216:219], v[52:55]
	v_mfma_f32_16x16x32_bf16 v[44:47], v[192:195], v[216:219], v[44:47]
	v_mfma_f32_16x16x32_bf16 v[48:51], v[154:157], v[224:227], v[48:51]
	v_mfma_f32_16x16x32_bf16 v[28:31], v[192:195], v[224:227], v[28:31]
	v_mfma_f32_16x16x32_bf16 v[32:35], v[154:157], v[232:235], v[32:35]
	v_mfma_f32_16x16x32_bf16 v[16:19], v[192:195], v[232:235], v[16:19]
	v_mfma_f32_16x16x32_bf16 v[130:133], v[154:157], v[240:243], v[132:135]
	v_mfma_f32_16x16x32_bf16 v[126:129], v[192:195], v[240:243], v[126:129]
	v_mfma_f32_16x16x32_bf16 v[52:55], v[188:191], v[220:223], v[52:55]
	v_mfma_f32_16x16x32_bf16 v[44:47], v[196:199], v[220:223], v[44:47]
	v_mfma_f32_16x16x32_bf16 v[48:51], v[188:191], v[228:231], v[48:51]
	v_mfma_f32_16x16x32_bf16 v[28:31], v[196:199], v[228:231], v[28:31]
	v_mfma_f32_16x16x32_bf16 v[32:35], v[188:191], v[236:239], v[32:35]
	v_mfma_f32_16x16x32_bf16 v[16:19], v[196:199], v[236:239], v[16:19]
	v_mfma_f32_16x16x32_bf16 v[132:135], v[188:191], v[244:247], v[130:133]
	v_mfma_f32_16x16x32_bf16 v[128:131], v[196:199], v[244:247], v[126:129]
	s_setprio 0
	s_setprio 1
	v_mfma_f32_16x16x32_bf16 v[40:43], v[200:203], v[216:219], v[40:43]
	v_mfma_f32_16x16x32_bf16 v[36:39], v[208:211], v[216:219], v[36:39]
	v_mfma_f32_16x16x32_bf16 v[24:27], v[200:203], v[224:227], v[24:27]
	v_mfma_f32_16x16x32_bf16 v[20:23], v[208:211], v[224:227], v[20:23]
	v_mfma_f32_16x16x32_bf16 v[12:15], v[200:203], v[232:235], v[12:15]
	v_mfma_f32_16x16x32_bf16 v[8:11], v[208:211], v[232:235], v[8:11]
	v_mfma_f32_16x16x32_bf16 v[0:3], v[200:203], v[240:243], v[0:3]
	v_mfma_f32_16x16x32_bf16 v[4:7], v[208:211], v[240:243], v[4:7]
	v_mfma_f32_16x16x32_bf16 v[40:43], v[204:207], v[220:223], v[40:43]
	v_mfma_f32_16x16x32_bf16 v[36:39], v[212:215], v[220:223], v[36:39]
	v_mfma_f32_16x16x32_bf16 v[24:27], v[204:207], v[228:231], v[24:27]
	v_mfma_f32_16x16x32_bf16 v[20:23], v[212:215], v[228:231], v[20:23]
	v_mfma_f32_16x16x32_bf16 v[12:15], v[204:207], v[236:239], v[12:15]
	v_mfma_f32_16x16x32_bf16 v[8:11], v[212:215], v[236:239], v[8:11]
	v_mfma_f32_16x16x32_bf16 v[0:3], v[204:207], v[244:247], v[0:3]
	v_mfma_f32_16x16x32_bf16 v[4:7], v[212:215], v[244:247], v[4:7]
	s_setprio 0
	s_barrier
	s_add_i32 s55, s55, 2
	s_add_u32 s26, s26, 0x100
	s_addc_u32 s27, s27, 0
	s_cmp_gt_u32 s55, 29
	s_cbranch_scc1 .LBB0_1025

.Lpeel_p4:
	v_add_u32_e32 v126, s48, v160
	ds_read_b128 v[154:157], v126
	ds_read_b128 v[188:191], v126 offset:1024
	ds_read_b128 v[192:195], v126 offset:2048
	ds_read_b128 v[196:199], v126 offset:3072
	v_add_u32_e32 v126, s49, v160
	s_add_u32 s28, s4, s26
	ds_read_b128 v[200:203], v126
	ds_read_b128 v[204:207], v126 offset:1024
	ds_read_b128 v[208:211], v126 offset:2048
	ds_read_b128 v[212:215], v126 offset:3072
	s_addc_u32 s29, s5, s27
	s_mov_b64 s[70:71], s[28:29]
	s_add_u32 s28, s28, 0x100
	s_addc_u32 s29, s29, 0
	s_add_u32 s56, s23, s26
	s_addc_u32 s57, s54, s27
	s_cmpk_eq_i32 s26, 0xf00
	s_cselect_b32 s31, s17, s29
	s_cselect_b32 s30, s52, s28
	s_cselect_b32 s29, s15, s57
	s_cselect_b32 s28, s53, s56
	s_add_i32 m0, s25, 0xc000
	ds_read_b128 v[216:219], v178
	ds_read_b128 v[220:223], v178 offset:1024
	ds_read_b128 v[224:227], v178 offset:2048
	ds_read_b128 v[228:231], v178 offset:3072
	ds_read_b128 v[232:235], v178 offset:4096
	ds_read_b128 v[236:239], v178 offset:5120
	ds_read_b128 v[240:243], v178 offset:6144
	ds_read_b128 v[244:247], v178 offset:7168
	global_load_lds_dwordx4 v150, s[70:71]
	s_add_i32 m0, s25, 0xe000
	s_nop 0
	global_load_lds_dwordx4 v152, s[70:71]
	s_waitcnt vmcnt(8)
	s_waitcnt lgkmcnt(0)
	s_barrier
	s_setprio 1
	s_waitcnt lgkmcnt(0)
	v_mfma_f32_16x16x32_bf16 v[116:119], v[154:157], v[216:219], 0
	v_mfma_f32_16x16x32_bf16 v[108:111], v[192:195], v[216:219], 0
	v_mfma_f32_16x16x32_bf16 v[112:115], v[154:157], v[224:227], 0
	v_mfma_f32_16x16x32_bf16 v[92:95], v[192:195], v[224:227], 0
	v_mfma_f32_16x16x32_bf16 v[96:99], v[154:157], v[232:235], 0
	v_mfma_f32_16x16x32_bf16 v[76:79], v[192:195], v[232:235], 0
	v_mfma_f32_16x16x32_bf16 v[80:83], v[154:157], v[240:243], 0
	v_mfma_f32_16x16x32_bf16 v[64:67], v[192:195], v[240:243], 0
	v_mfma_f32_16x16x32_bf16 v[116:119], v[188:191], v[220:223], v[116:119]
	v_mfma_f32_16x16x32_bf16 v[108:111], v[196:199], v[220:223], v[108:111]
	v_mfma_f32_16x16x32_bf16 v[112:115], v[188:191], v[228:231], v[112:115]
	v_mfma_f32_16x16x32_bf16 v[92:95], v[196:199], v[228:231], v[92:95]
	v_mfma_f32_16x16x32_bf16 v[96:99], v[188:191], v[236:239], v[96:99]
	v_mfma_f32_16x16x32_bf16 v[76:79], v[196:199], v[236:239], v[76:79]
	v_mfma_f32_16x16x32_bf16 v[80:83], v[188:191], v[244:247], v[80:83]
	v_mfma_f32_16x16x32_bf16 v[64:67], v[196:199], v[244:247], v[64:67]
	s_setprio 0
	s_setprio 1
	v_mfma_f32_16x16x32_bf16 v[104:107], v[200:203], v[216:219], 0
	v_mfma_f32_16x16x32_bf16 v[100:103], v[208:211], v[216:219], 0
	v_mfma_f32_16x16x32_bf16 v[88:91], v[200:203], v[224:227], 0
	v_mfma_f32_16x16x32_bf16 v[84:87], v[208:211], v[224:227], 0
	v_mfma_f32_16x16x32_bf16 v[72:75], v[200:203], v[232:235], 0
	v_mfma_f32_16x16x32_bf16 v[68:71], v[208:211], v[232:235], 0
	v_mfma_f32_16x16x32_bf16 v[60:63], v[200:203], v[240:243], 0
	v_mfma_f32_16x16x32_bf16 v[56:59], v[208:211], v[240:243], 0
	v_mfma_f32_16x16x32_bf16 v[104:107], v[204:207], v[220:223], v[104:107]
	v_mfma_f32_16x16x32_bf16 v[100:103], v[212:215], v[220:223], v[100:103]
	v_mfma_f32_16x16x32_bf16 v[88:91], v[204:207], v[228:231], v[88:91]
	v_mfma_f32_16x16x32_bf16 v[84:87], v[212:215], v[228:231], v[84:87]
	v_mfma_f32_16x16x32_bf16 v[72:75], v[204:207], v[236:239], v[72:75]
	v_mfma_f32_16x16x32_bf16 v[68:71], v[212:215], v[236:239], v[68:71]
	v_mfma_f32_16x16x32_bf16 v[60:63], v[204:207], v[244:247], v[60:63]
	v_mfma_f32_16x16x32_bf16 v[56:59], v[212:215], v[244:247], v[56:59]
	s_setprio 0
	s_barrier
	s_add_i32 s56, s48, s36
	s_add_u32 s74, s28, 0x80
	s_addc_u32 s75, s29, 0
	s_mov_b32 m0, s56
	ds_read_b128 v[216:219], v178 offset:16384
	ds_read_b128 v[220:223], v178 offset:17408
	ds_read_b128 v[224:227], v178 offset:18432
	ds_read_b128 v[228:231], v178 offset:19456
	ds_read_b128 v[232:235], v178 offset:20480
	ds_read_b128 v[236:239], v178 offset:21504
	ds_read_b128 v[240:243], v178 offset:22528
	ds_read_b128 v[244:247], v178 offset:23552
	global_load_lds_dwordx4 v138, s[28:29]
	s_add_i32 m0, s56, 0x2000
	s_add_u32 s56, s28, 0x80000
	s_addc_u32 s57, s29, 0
	s_add_i32 s58, s49, s36
	global_load_lds_dwordx4 v142, s[28:29]
	s_mov_b32 m0, s58
	s_add_u32 s78, s30, 0x80
	s_addc_u32 s79, s31, 0
	global_load_lds_dwordx4 v138, s[56:57]
	s_add_i32 m0, s58, 0x2000
	s_nop 0
	global_load_lds_dwordx4 v142, s[56:57]
	s_mov_b32 m0, s25
	s_nop 0
	global_load_lds_dwordx4 v136, s[30:31]
	s_mov_b32 m0, s39
	s_nop 0
	global_load_lds_dwordx4 v140, s[30:31]
	s_waitcnt vmcnt(8)
	s_waitcnt lgkmcnt(0)
	s_barrier
	s_setprio 1
	s_waitcnt lgkmcnt(0)
	v_mfma_f32_16x16x32_bf16 v[52:55], v[154:157], v[216:219], 0
	v_mfma_f32_16x16x32_bf16 v[44:47], v[192:195], v[216:219], 0
	v_mfma_f32_16x16x32_bf16 v[48:51], v[154:157], v[224:227], 0
	v_mfma_f32_16x16x32_bf16 v[28:31], v[192:195], v[224:227], 0
	v_mfma_f32_16x16x32_bf16 v[32:35], v[154:157], v[232:235], 0
	v_mfma_f32_16x16x32_bf16 v[16:19], v[192:195], v[232:235], 0
	v_mfma_f32_16x16x32_bf16 v[132:135], v[154:157], v[240:243], 0
	v_mfma_f32_16x16x32_bf16 v[126:129], v[192:195], v[240:243], 0
	v_mfma_f32_16x16x32_bf16 v[52:55], v[188:191], v[220:223], v[52:55]
	v_mfma_f32_16x16x32_bf16 v[44:47], v[196:199], v[220:223], v[44:47]
	v_mfma_f32_16x16x32_bf16 v[48:51], v[188:191], v[228:231], v[48:51]
	v_mfma_f32_16x16x32_bf16 v[28:31], v[196:199], v[228:231], v[28:31]
	v_mfma_f32_16x16x32_bf16 v[32:35], v[188:191], v[236:239], v[32:35]
	v_mfma_f32_16x16x32_bf16 v[16:19], v[196:199], v[236:239], v[16:19]
	v_mfma_f32_16x16x32_bf16 v[132:135], v[188:191], v[244:247], v[132:135]
	v_mfma_f32_16x16x32_bf16 v[126:129], v[196:199], v[244:247], v[126:129]
	s_setprio 0
	s_setprio 1
	v_mfma_f32_16x16x32_bf16 v[40:43], v[200:203], v[216:219], 0
	v_mfma_f32_16x16x32_bf16 v[36:39], v[208:211], v[216:219], 0
	v_mfma_f32_16x16x32_bf16 v[24:27], v[200:203], v[224:227], 0
	v_mfma_f32_16x16x32_bf16 v[20:23], v[208:211], v[224:227], 0
	v_mfma_f32_16x16x32_bf16 v[12:15], v[200:203], v[232:235], 0
	v_mfma_f32_16x16x32_bf16 v[8:11], v[208:211], v[232:235], 0
	v_mfma_f32_16x16x32_bf16 v[0:3], v[200:203], v[240:243], 0
	v_mfma_f32_16x16x32_bf16 v[4:7], v[208:211], v[240:243], 0
	v_mfma_f32_16x16x32_bf16 v[40:43], v[204:207], v[220:223], v[40:43]
	v_mfma_f32_16x16x32_bf16 v[36:39], v[212:215], v[220:223], v[36:39]
	v_mfma_f32_16x16x32_bf16 v[24:27], v[204:207], v[228:231], v[24:27]
	v_mfma_f32_16x16x32_bf16 v[20:23], v[212:215], v[228:231], v[20:23]
	v_mfma_f32_16x16x32_bf16 v[12:15], v[204:207], v[236:239], v[12:15]
	v_mfma_f32_16x16x32_bf16 v[8:11], v[212:215], v[236:239], v[8:11]
	v_mfma_f32_16x16x32_bf16 v[0:3], v[204:207], v[244:247], v[0:3]
	v_mfma_f32_16x16x32_bf16 v[4:7], v[212:215], v[244:247], v[4:7]
	s_setprio 0
	s_barrier
	s_add_i32 s56, 0, 0x18000
	v_add_u32_e32 v130, s56, v160
	s_add_i32 s57, 0, 0x1c000
	ds_read_b128 v[154:157], v130
	ds_read_b128 v[188:191], v130 offset:1024
	ds_read_b128 v[192:195], v130 offset:2048
	ds_read_b128 v[196:199], v130 offset:3072
	v_add_u32_e32 v130, s57, v160
	ds_read_b128 v[200:203], v130
	ds_read_b128 v[204:207], v130 offset:1024
	ds_read_b128 v[208:211], v130 offset:2048
	ds_read_b128 v[212:215], v130 offset:3072
	s_add_u32 s30, s30, 0x80000
	s_addc_u32 s31, s31, 0
	s_mov_b32 m0, s40
	ds_read_b128 v[216:219], v178 offset:32768
	ds_read_b128 v[220:223], v178 offset:33792
	ds_read_b128 v[224:227], v178 offset:34816
	ds_read_b128 v[228:231], v178 offset:35840
	ds_read_b128 v[232:235], v178 offset:36864
	ds_read_b128 v[236:239], v178 offset:37888
	ds_read_b128 v[240:243], v178 offset:38912
	ds_read_b128 v[244:247], v178 offset:39936
	global_load_lds_dwordx4 v136, s[30:31]
	s_mov_b32 m0, s41
	s_nop 0
	global_load_lds_dwordx4 v140, s[30:31]
	s_waitcnt vmcnt(8)
	s_waitcnt lgkmcnt(0)
	s_barrier
	s_setprio 1
	s_waitcnt lgkmcnt(0)
	v_mfma_f32_16x16x32_bf16 v[116:119], v[154:157], v[216:219], v[116:119]
	v_mfma_f32_16x16x32_bf16 v[108:111], v[192:195], v[216:219], v[108:111]
	v_mfma_f32_16x16x32_bf16 v[112:115], v[154:157], v[224:227], v[112:115]
	v_mfma_f32_16x16x32_bf16 v[92:95], v[192:195], v[224:227], v[92:95]
	v_mfma_f32_16x16x32_bf16 v[96:99], v[154:157], v[232:235], v[96:99]
	v_mfma_f32_16x16x32_bf16 v[76:79], v[192:195], v[232:235], v[76:79]
	v_mfma_f32_16x16x32_bf16 v[80:83], v[154:157], v[240:243], v[80:83]
	v_mfma_f32_16x16x32_bf16 v[64:67], v[192:195], v[240:243], v[64:67]
	v_mfma_f32_16x16x32_bf16 v[116:119], v[188:191], v[220:223], v[116:119]
	v_mfma_f32_16x16x32_bf16 v[108:111], v[196:199], v[220:223], v[108:111]
	v_mfma_f32_16x16x32_bf16 v[112:115], v[188:191], v[228:231], v[112:115]
	v_mfma_f32_16x16x32_bf16 v[92:95], v[196:199], v[228:231], v[92:95]
	v_mfma_f32_16x16x32_bf16 v[96:99], v[188:191], v[236:239], v[96:99]
	v_mfma_f32_16x16x32_bf16 v[76:79], v[196:199], v[236:239], v[76:79]
	v_mfma_f32_16x16x32_bf16 v[80:83], v[188:191], v[244:247], v[80:83]
	v_mfma_f32_16x16x32_bf16 v[64:67], v[196:199], v[244:247], v[64:67]
	s_setprio 0
	s_setprio 1
	v_mfma_f32_16x16x32_bf16 v[104:107], v[200:203], v[216:219], v[104:107]
	v_mfma_f32_16x16x32_bf16 v[100:103], v[208:211], v[216:219], v[100:103]
	v_mfma_f32_16x16x32_bf16 v[88:91], v[200:203], v[224:227], v[88:91]
	v_mfma_f32_16x16x32_bf16 v[84:87], v[208:211], v[224:227], v[84:87]
	v_mfma_f32_16x16x32_bf16 v[72:75], v[200:203], v[232:235], v[72:75]
	v_mfma_f32_16x16x32_bf16 v[68:71], v[208:211], v[232:235], v[68:71]
	v_mfma_f32_16x16x32_bf16 v[60:63], v[200:203], v[240:243], v[60:63]
	v_mfma_f32_16x16x32_bf16 v[56:59], v[208:211], v[240:243], v[56:59]
	v_mfma_f32_16x16x32_bf16 v[104:107], v[204:207], v[220:223], v[104:107]
	v_mfma_f32_16x16x32_bf16 v[100:103], v[212:215], v[220:223], v[100:103]
	v_mfma_f32_16x16x32_bf16 v[88:91], v[204:207], v[228:231], v[88:91]
	v_mfma_f32_16x16x32_bf16 v[84:87], v[212:215], v[228:231], v[84:87]
	v_mfma_f32_16x16x32_bf16 v[72:75], v[204:207], v[236:239], v[72:75]
	v_mfma_f32_16x16x32_bf16 v[68:71], v[212:215], v[236:239], v[68:71]
	v_mfma_f32_16x16x32_bf16 v[60:63], v[204:207], v[244:247], v[60:63]
	v_mfma_f32_16x16x32_bf16 v[56:59], v[212:215], v[244:247], v[56:59]
	s_setprio 0
	s_barrier
	s_add_i32 s30, s56, s36
	s_mov_b32 m0, s30
	ds_read_b128 v[216:219], v178 offset:49152
	ds_read_b128 v[220:223], v178 offset:50176
	ds_read_b128 v[224:227], v178 offset:51200
	ds_read_b128 v[228:231], v178 offset:52224
	ds_read_b128 v[232:235], v178 offset:53248
	ds_read_b128 v[236:239], v178 offset:54272
	ds_read_b128 v[240:243], v178 offset:55296
	ds_read_b128 v[244:247], v178 offset:56320
	global_load_lds_dwordx4 v138, s[74:75]
	s_add_i32 m0, s30, 0x2000
	s_add_u32 s28, s28, 0x80080
	s_addc_u32 s29, s29, 0
	s_add_i32 s30, s57, s36
	global_load_lds_dwordx4 v142, s[74:75]
	s_mov_b32 m0, s30
	s_nop 0
	global_load_lds_dwordx4 v138, s[28:29]
	s_add_i32 m0, s30, 0x2000
	s_nop 0
	global_load_lds_dwordx4 v142, s[28:29]
	s_mov_b32 m0, s44
	s_nop 0
	global_load_lds_dwordx4 v136, s[78:79]
	s_mov_b32 m0, s45
	s_nop 0
	global_load_lds_dwordx4 v140, s[78:79]
	s_waitcnt vmcnt(8)
	s_waitcnt lgkmcnt(0)
	s_barrier
	s_setprio 1
	s_waitcnt lgkmcnt(0)
	v_mfma_f32_16x16x32_bf16 v[52:55], v[154:157], v[216:219], v[52:55]
	v_mfma_f32_16x16x32_bf16 v[44:47], v[192:195], v[216:219], v[44:47]
	v_mfma_f32_16x16x32_bf16 v[48:51], v[154:157], v[224:227], v[48:51]
	v_mfma_f32_16x16x32_bf16 v[28:31], v[192:195], v[224:227], v[28:31]
	v_mfma_f32_16x16x32_bf16 v[32:35], v[154:157], v[232:235], v[32:35]
	v_mfma_f32_16x16x32_bf16 v[16:19], v[192:195], v[232:235], v[16:19]
	v_mfma_f32_16x16x32_bf16 v[130:133], v[154:157], v[240:243], v[132:135]
	v_mfma_f32_16x16x32_bf16 v[126:129], v[192:195], v[240:243], v[126:129]
	v_mfma_f32_16x16x32_bf16 v[52:55], v[188:191], v[220:223], v[52:55]
	v_mfma_f32_16x16x32_bf16 v[44:47], v[196:199], v[220:223], v[44:47]
	v_mfma_f32_16x16x32_bf16 v[48:51], v[188:191], v[228:231], v[48:51]
	v_mfma_f32_16x16x32_bf16 v[28:31], v[196:199], v[228:231], v[28:31]
	v_mfma_f32_16x16x32_bf16 v[32:35], v[188:191], v[236:239], v[32:35]
	v_mfma_f32_16x16x32_bf16 v[16:19], v[196:199], v[236:239], v[16:19]
	v_mfma_f32_16x16x32_bf16 v[132:135], v[188:191], v[244:247], v[130:133]
	v_mfma_f32_16x16x32_bf16 v[128:131], v[196:199], v[244:247], v[126:129]
	s_setprio 0
	s_setprio 1
	v_mfma_f32_16x16x32_bf16 v[40:43], v[200:203], v[216:219], v[40:43]
	v_mfma_f32_16x16x32_bf16 v[36:39], v[208:211], v[216:219], v[36:39]
	v_mfma_f32_16x16x32_bf16 v[24:27], v[200:203], v[224:227], v[24:27]
	v_mfma_f32_16x16x32_bf16 v[20:23], v[208:211], v[224:227], v[20:23]
	v_mfma_f32_16x16x32_bf16 v[12:15], v[200:203], v[232:235], v[12:15]
	v_mfma_f32_16x16x32_bf16 v[8:11], v[208:211], v[232:235], v[8:11]
	v_mfma_f32_16x16x32_bf16 v[0:3], v[200:203], v[240:243], v[0:3]
	v_mfma_f32_16x16x32_bf16 v[4:7], v[208:211], v[240:243], v[4:7]
	v_mfma_f32_16x16x32_bf16 v[40:43], v[204:207], v[220:223], v[40:43]
	v_mfma_f32_16x16x32_bf16 v[36:39], v[212:215], v[220:223], v[36:39]
	v_mfma_f32_16x16x32_bf16 v[24:27], v[204:207], v[228:231], v[24:27]
	v_mfma_f32_16x16x32_bf16 v[20:23], v[212:215], v[228:231], v[20:23]
	v_mfma_f32_16x16x32_bf16 v[12:15], v[204:207], v[236:239], v[12:15]
	v_mfma_f32_16x16x32_bf16 v[8:11], v[212:215], v[236:239], v[8:11]
	v_mfma_f32_16x16x32_bf16 v[0:3], v[204:207], v[244:247], v[0:3]
	v_mfma_f32_16x16x32_bf16 v[4:7], v[212:215], v[244:247], v[4:7]
	s_setprio 0
	s_barrier
	s_add_i32 s55, s55, 2
	s_add_u32 s26, s26, 0x100
	s_addc_u32 s27, s27, 0
	s_cmp_gt_u32 s55, 29
	s_cbranch_scc1 .LBB0_1025
	s_branch .LBB0_1023

.LBB0_1449:
.LBB0_1450:
	s_nop 0
	s_cmp_lt_i32 s92, 7
	s_cselect_b64 s[0:1], -1, 0
	s_cmp_gt_i32 s93, 6
	s_cselect_b64 s[2:3], -1, 0
	s_and_b64 s[0:1], s[0:1], s[2:3]
	s_andn2_b64 vcc, exec, s[0:1]
	s_cbranch_vccnz .LBB0_1475
	v_readlane_b32 s0, v254, 24
	s_andn2_b32 s0, s0, 63
	v_mbcnt_lo_u32_b32 v8, -1, 0
	v_mbcnt_hi_u32_b32 v8, -1, v8
	s_cmpk_gt_i32 s69, 0x1ff
	v_add_u32_e32 v0, s0, v8
	s_nop 0
	v_readfirstlane_b32 s8, v0
	s_cbranch_scc1 .LBB0_1475
	s_ashr_i32 s26, s69, 31
	s_lshr_b32 s0, s26, 29
	s_add_i32 s4, s69, s0
	s_and_b32 s0, s4, -8
	s_sub_i32 s3, s69, s0
	s_cmp_gt_i32 s3, -1
	s_cbranch_scc0 .LBB0_1454
	s_lshl_b32 s2, s3, 6
	s_ashr_i32 s0, s4, 3
	s_cbranch_execz .LBB0_1455
	s_branch .LBB0_1456

.LBB0_1467:
	s_ashr_i32 s13, s12, 31
	s_lshl_b64 s[14:15], s[12:13], 20
	s_add_u32 s14, s27, s14
	s_addc_u32 s15, s28, s15
	s_and_b64 s[16:17], s[0:1], exec
	s_cselect_b32 s13, s15, s21
	s_cselect_b32 s43, s14, s20
	s_ashr_i32 s11, s10, 31
	s_lshl_b64 s[16:17], s[10:11], 20
	s_add_u32 s16, s29, s16
	s_addc_u32 s17, s30, s17
	s_and_b64 s[24:25], s[0:1], exec
	s_cselect_b32 s11, s17, s23
	s_cselect_b32 s44, s16, s22
	s_add_u32 s20, s20, 0x80080
	s_addc_u32 s21, s21, 0
	s_add_u32 s45, s22, 0x100
	s_addc_u32 s46, s23, 0
	s_mov_b32 s47, -2
	ds_read_b128 v[144:147], v151
	ds_read_b128 v[154:157], v151 offset:1024
	ds_read_b128 v[158:161], v151 offset:2048
	ds_read_b128 v[162:165], v151 offset:3072
	ds_read_b128 v[166:169], v152
	ds_read_b128 v[170:173], v152 offset:1024
	ds_read_b128 v[174:177], v152 offset:2048
	ds_read_b128 v[178:181], v152 offset:3072
	s_add_u32 s22, s20, 0xfff80080
	s_addc_u32 s23, s21, -1
	s_cmp_eq_u32 s47, 28
	s_cselect_b32 s25, s13, s23
	s_cselect_b32 s24, s43, s22
	s_cselect_b32 s23, s11, s46
	s_cselect_b32 s22, s44, s45
	s_add_i32 m0, s19, 0xc000
	ds_read_b128 v[182:185], v153
	ds_read_b128 v[186:189], v153 offset:1024
	ds_read_b128 v[190:193], v153 offset:2048
	ds_read_b128 v[194:197], v153 offset:3072
	ds_read_b128 v[198:201], v153 offset:4096
	ds_read_b128 v[202:205], v153 offset:5120
	ds_read_b128 v[206:209], v153 offset:6144
	ds_read_b128 v[210:213], v153 offset:7168
	global_load_lds_dwordx4 v136, s[20:21]
	s_add_i32 m0, s19, 0xe000
	s_nop 0
	global_load_lds_dwordx4 v138, s[20:21]
	s_waitcnt vmcnt(8)
	s_waitcnt lgkmcnt(0)
	s_barrier
	s_setprio 1
	s_waitcnt lgkmcnt(0)
	v_mfma_f32_16x16x32_bf16 v[124:127], v[144:147], v[182:185], 0
	v_mfma_f32_16x16x32_bf16 v[120:123], v[158:161], v[182:185], 0
	v_mfma_f32_16x16x32_bf16 v[108:111], v[144:147], v[190:193], 0
	v_mfma_f32_16x16x32_bf16 v[104:107], v[158:161], v[190:193], 0
	v_mfma_f32_16x16x32_bf16 v[92:95], v[144:147], v[198:201], 0
	v_mfma_f32_16x16x32_bf16 v[88:91], v[158:161], v[198:201], 0
	v_mfma_f32_16x16x32_bf16 v[76:79], v[144:147], v[206:209], 0
	v_mfma_f32_16x16x32_bf16 v[72:75], v[158:161], v[206:209], 0
	v_mfma_f32_16x16x32_bf16 v[124:127], v[154:157], v[186:189], v[124:127]
	v_mfma_f32_16x16x32_bf16 v[120:123], v[162:165], v[186:189], v[120:123]
	v_mfma_f32_16x16x32_bf16 v[108:111], v[154:157], v[194:197], v[108:111]
	v_mfma_f32_16x16x32_bf16 v[104:107], v[162:165], v[194:197], v[104:107]
	v_mfma_f32_16x16x32_bf16 v[92:95], v[154:157], v[202:205], v[92:95]
	v_mfma_f32_16x16x32_bf16 v[88:91], v[162:165], v[202:205], v[88:91]
	v_mfma_f32_16x16x32_bf16 v[76:79], v[154:157], v[210:213], v[76:79]
	v_mfma_f32_16x16x32_bf16 v[72:75], v[162:165], v[210:213], v[72:75]
	s_setprio 0
	s_setprio 1
	v_mfma_f32_16x16x32_bf16 v[116:119], v[166:169], v[182:185], 0
	v_mfma_f32_16x16x32_bf16 v[112:115], v[174:177], v[182:185], 0
	v_mfma_f32_16x16x32_bf16 v[100:103], v[166:169], v[190:193], 0
	v_mfma_f32_16x16x32_bf16 v[96:99], v[174:177], v[190:193], 0
	v_mfma_f32_16x16x32_bf16 v[84:87], v[166:169], v[198:201], 0
	v_mfma_f32_16x16x32_bf16 v[80:83], v[174:177], v[198:201], 0
	v_mfma_f32_16x16x32_bf16 v[68:71], v[166:169], v[206:209], 0
	v_mfma_f32_16x16x32_bf16 v[64:67], v[174:177], v[206:209], 0
	v_mfma_f32_16x16x32_bf16 v[116:119], v[170:173], v[186:189], v[116:119]
	v_mfma_f32_16x16x32_bf16 v[112:115], v[178:181], v[186:189], v[112:115]
	v_mfma_f32_16x16x32_bf16 v[100:103], v[170:173], v[194:197], v[100:103]
	v_mfma_f32_16x16x32_bf16 v[96:99], v[178:181], v[194:197], v[96:99]
	v_mfma_f32_16x16x32_bf16 v[84:87], v[170:173], v[202:205], v[84:87]
	v_mfma_f32_16x16x32_bf16 v[80:83], v[178:181], v[202:205], v[80:83]
	v_mfma_f32_16x16x32_bf16 v[68:71], v[170:173], v[210:213], v[68:71]
	v_mfma_f32_16x16x32_bf16 v[64:67], v[178:181], v[210:213], v[64:67]
	s_setprio 0
	s_barrier
	s_add_i32 s48, s40, s31
	s_add_u32 s70, s22, 0x80
	s_addc_u32 s71, s23, 0
	s_mov_b32 m0, s48
	ds_read_b128 v[182:185], v153 offset:16384
	ds_read_b128 v[186:189], v153 offset:17408
	ds_read_b128 v[190:193], v153 offset:18432
	ds_read_b128 v[194:197], v153 offset:19456
	ds_read_b128 v[198:201], v153 offset:20480
	ds_read_b128 v[202:205], v153 offset:21504
	ds_read_b128 v[206:209], v153 offset:22528
	ds_read_b128 v[210:213], v153 offset:23552
	global_load_lds_dwordx4 v130, s[22:23]
	s_add_i32 m0, s48, 0x2000
	s_add_u32 s48, s22, 0x80000
	s_addc_u32 s49, s23, 0
	s_add_i32 s50, s41, s31
	global_load_lds_dwordx4 v134, s[22:23]
	s_mov_b32 m0, s50
	s_nop 0
	global_load_lds_dwordx4 v130, s[48:49]
	s_add_i32 m0, s50, 0x2000
	s_nop 0
	global_load_lds_dwordx4 v134, s[48:49]
	s_add_u32 s74, s24, 0x80
	s_addc_u32 s75, s25, 0
	s_mov_b32 m0, s19
	s_nop 0
	global_load_lds_dwordx4 v128, s[24:25]
	s_mov_b32 m0, s33
	s_nop 0
	global_load_lds_dwordx4 v132, s[24:25]
	s_waitcnt vmcnt(8)
	s_waitcnt lgkmcnt(0)
	s_barrier
	s_setprio 1
	s_waitcnt lgkmcnt(0)
	v_mfma_f32_16x16x32_bf16 v[60:63], v[144:147], v[182:185], 0
	v_mfma_f32_16x16x32_bf16 v[56:59], v[158:161], v[182:185], 0
	v_mfma_f32_16x16x32_bf16 v[44:47], v[144:147], v[190:193], 0
	v_mfma_f32_16x16x32_bf16 v[40:43], v[158:161], v[190:193], 0
	v_mfma_f32_16x16x32_bf16 v[28:31], v[144:147], v[198:201], 0
	v_mfma_f32_16x16x32_bf16 v[24:27], v[158:161], v[198:201], 0
	v_mfma_f32_16x16x32_bf16 v[12:15], v[144:147], v[206:209], 0
	v_mfma_f32_16x16x32_bf16 v[8:11], v[158:161], v[206:209], 0
	v_mfma_f32_16x16x32_bf16 v[60:63], v[154:157], v[186:189], v[60:63]
	v_mfma_f32_16x16x32_bf16 v[56:59], v[162:165], v[186:189], v[56:59]
	v_mfma_f32_16x16x32_bf16 v[44:47], v[154:157], v[194:197], v[44:47]
	v_mfma_f32_16x16x32_bf16 v[40:43], v[162:165], v[194:197], v[40:43]
	v_mfma_f32_16x16x32_bf16 v[28:31], v[154:157], v[202:205], v[28:31]
	v_mfma_f32_16x16x32_bf16 v[24:27], v[162:165], v[202:205], v[24:27]
	v_mfma_f32_16x16x32_bf16 v[12:15], v[154:157], v[210:213], v[12:15]
	v_mfma_f32_16x16x32_bf16 v[8:11], v[162:165], v[210:213], v[8:11]
	s_setprio 0
	s_setprio 1
	v_mfma_f32_16x16x32_bf16 v[52:55], v[166:169], v[182:185], 0
	v_mfma_f32_16x16x32_bf16 v[48:51], v[174:177], v[182:185], 0
	v_mfma_f32_16x16x32_bf16 v[36:39], v[166:169], v[190:193], 0
	v_mfma_f32_16x16x32_bf16 v[32:35], v[174:177], v[190:193], 0
	v_mfma_f32_16x16x32_bf16 v[20:23], v[166:169], v[198:201], 0
	v_mfma_f32_16x16x32_bf16 v[16:19], v[174:177], v[198:201], 0
	v_mfma_f32_16x16x32_bf16 v[4:7], v[166:169], v[206:209], 0
	v_mfma_f32_16x16x32_bf16 v[0:3], v[174:177], v[206:209], 0
	v_mfma_f32_16x16x32_bf16 v[52:55], v[170:173], v[186:189], v[52:55]
	v_mfma_f32_16x16x32_bf16 v[48:51], v[178:181], v[186:189], v[48:51]
	v_mfma_f32_16x16x32_bf16 v[36:39], v[170:173], v[194:197], v[36:39]
	v_mfma_f32_16x16x32_bf16 v[32:35], v[178:181], v[194:197], v[32:35]
	v_mfma_f32_16x16x32_bf16 v[20:23], v[170:173], v[202:205], v[20:23]
	v_mfma_f32_16x16x32_bf16 v[16:19], v[178:181], v[202:205], v[16:19]
	v_mfma_f32_16x16x32_bf16 v[4:7], v[170:173], v[210:213], v[4:7]
	v_mfma_f32_16x16x32_bf16 v[0:3], v[178:181], v[210:213], v[0:3]
	s_setprio 0
	s_barrier
	s_add_i32 s48, 0, 0x18000
	s_add_i32 s49, 0, 0x1c000
	v_add_u32_e32 v162, s48, v149
	v_add_u32_e32 v178, s49, v149
	ds_read_b128 v[144:147], v162
	ds_read_b128 v[154:157], v162 offset:1024
	ds_read_b128 v[158:161], v162 offset:2048
	ds_read_b128 v[162:165], v162 offset:3072
	ds_read_b128 v[166:169], v178
	ds_read_b128 v[170:173], v178 offset:1024
	ds_read_b128 v[174:177], v178 offset:2048
	ds_read_b128 v[178:181], v178 offset:3072
	s_add_u32 s24, s24, 0x80000
	s_addc_u32 s25, s25, 0
	s_mov_b32 m0, s34
	ds_read_b128 v[182:185], v153 offset:32768
	ds_read_b128 v[186:189], v153 offset:33792
	ds_read_b128 v[190:193], v153 offset:34816
	ds_read_b128 v[194:197], v153 offset:35840
	ds_read_b128 v[198:201], v153 offset:36864
	ds_read_b128 v[202:205], v153 offset:37888
	ds_read_b128 v[206:209], v153 offset:38912
	ds_read_b128 v[210:213], v153 offset:39936
	global_load_lds_dwordx4 v128, s[24:25]
	s_mov_b32 m0, s35
	s_nop 0
	global_load_lds_dwordx4 v132, s[24:25]
	s_waitcnt vmcnt(8)
	s_waitcnt lgkmcnt(0)
	s_barrier
	s_setprio 1
	s_waitcnt lgkmcnt(0)
	v_mfma_f32_16x16x32_bf16 v[124:127], v[144:147], v[182:185], v[124:127]
	v_mfma_f32_16x16x32_bf16 v[120:123], v[158:161], v[182:185], v[120:123]
	v_mfma_f32_16x16x32_bf16 v[108:111], v[144:147], v[190:193], v[108:111]
	v_mfma_f32_16x16x32_bf16 v[104:107], v[158:161], v[190:193], v[104:107]
	v_mfma_f32_16x16x32_bf16 v[92:95], v[144:147], v[198:201], v[92:95]
	v_mfma_f32_16x16x32_bf16 v[88:91], v[158:161], v[198:201], v[88:91]
	v_mfma_f32_16x16x32_bf16 v[76:79], v[144:147], v[206:209], v[76:79]
	v_mfma_f32_16x16x32_bf16 v[72:75], v[158:161], v[206:209], v[72:75]
	v_mfma_f32_16x16x32_bf16 v[124:127], v[154:157], v[186:189], v[124:127]
	v_mfma_f32_16x16x32_bf16 v[120:123], v[162:165], v[186:189], v[120:123]
	v_mfma_f32_16x16x32_bf16 v[108:111], v[154:157], v[194:197], v[108:111]
	v_mfma_f32_16x16x32_bf16 v[104:107], v[162:165], v[194:197], v[104:107]
	v_mfma_f32_16x16x32_bf16 v[92:95], v[154:157], v[202:205], v[92:95]
	v_mfma_f32_16x16x32_bf16 v[88:91], v[162:165], v[202:205], v[88:91]
	v_mfma_f32_16x16x32_bf16 v[76:79], v[154:157], v[210:213], v[76:79]
	v_mfma_f32_16x16x32_bf16 v[72:75], v[162:165], v[210:213], v[72:75]
	s_setprio 0
	s_setprio 1
	v_mfma_f32_16x16x32_bf16 v[116:119], v[166:169], v[182:185], v[116:119]
	v_mfma_f32_16x16x32_bf16 v[112:115], v[174:177], v[182:185], v[112:115]
	v_mfma_f32_16x16x32_bf16 v[100:103], v[166:169], v[190:193], v[100:103]
	v_mfma_f32_16x16x32_bf16 v[96:99], v[174:177], v[190:193], v[96:99]
	v_mfma_f32_16x16x32_bf16 v[84:87], v[166:169], v[198:201], v[84:87]
	v_mfma_f32_16x16x32_bf16 v[80:83], v[174:177], v[198:201], v[80:83]
	v_mfma_f32_16x16x32_bf16 v[68:71], v[166:169], v[206:209], v[68:71]
	v_mfma_f32_16x16x32_bf16 v[64:67], v[174:177], v[206:209], v[64:67]
	v_mfma_f32_16x16x32_bf16 v[116:119], v[170:173], v[186:189], v[116:119]
	v_mfma_f32_16x16x32_bf16 v[112:115], v[178:181], v[186:189], v[112:115]
	v_mfma_f32_16x16x32_bf16 v[100:103], v[170:173], v[194:197], v[100:103]
	v_mfma_f32_16x16x32_bf16 v[96:99], v[178:181], v[194:197], v[96:99]
	v_mfma_f32_16x16x32_bf16 v[84:87], v[170:173], v[202:205], v[84:87]
	v_mfma_f32_16x16x32_bf16 v[80:83], v[178:181], v[202:205], v[80:83]
	v_mfma_f32_16x16x32_bf16 v[68:71], v[170:173], v[210:213], v[68:71]
	v_mfma_f32_16x16x32_bf16 v[64:67], v[178:181], v[210:213], v[64:67]
	s_setprio 0
	s_barrier
	s_add_i32 s24, s48, s31
	s_mov_b32 m0, s24
	ds_read_b128 v[182:185], v153 offset:49152
	ds_read_b128 v[186:189], v153 offset:50176
	ds_read_b128 v[190:193], v153 offset:51200
	ds_read_b128 v[194:197], v153 offset:52224
	ds_read_b128 v[198:201], v153 offset:53248
	ds_read_b128 v[202:205], v153 offset:54272
	ds_read_b128 v[206:209], v153 offset:55296
	ds_read_b128 v[210:213], v153 offset:56320
	global_load_lds_dwordx4 v130, s[70:71]
	s_add_i32 m0, s24, 0x2000
	s_add_u32 s22, s22, 0x80080
	s_addc_u32 s23, s23, 0
	s_add_i32 s24, s49, s31
	global_load_lds_dwordx4 v134, s[70:71]
	s_mov_b32 m0, s24
	s_nop 0
	global_load_lds_dwordx4 v130, s[22:23]
	s_add_i32 m0, s24, 0x2000
	s_nop 0
	global_load_lds_dwordx4 v134, s[22:23]
	s_mov_b32 m0, s37
	s_nop 0
	global_load_lds_dwordx4 v128, s[74:75]
	s_mov_b32 m0, s38
	s_nop 0
	global_load_lds_dwordx4 v132, s[74:75]
	s_waitcnt vmcnt(8)
	s_waitcnt lgkmcnt(0)
	s_barrier
	s_setprio 1
	s_waitcnt lgkmcnt(0)
	v_mfma_f32_16x16x32_bf16 v[60:63], v[144:147], v[182:185], v[60:63]
	v_mfma_f32_16x16x32_bf16 v[56:59], v[158:161], v[182:185], v[56:59]
	v_mfma_f32_16x16x32_bf16 v[44:47], v[144:147], v[190:193], v[44:47]
	v_mfma_f32_16x16x32_bf16 v[40:43], v[158:161], v[190:193], v[40:43]
	v_mfma_f32_16x16x32_bf16 v[28:31], v[144:147], v[198:201], v[28:31]
	v_mfma_f32_16x16x32_bf16 v[24:27], v[158:161], v[198:201], v[24:27]
	v_mfma_f32_16x16x32_bf16 v[12:15], v[144:147], v[206:209], v[12:15]
	v_mfma_f32_16x16x32_bf16 v[8:11], v[158:161], v[206:209], v[8:11]
	v_mfma_f32_16x16x32_bf16 v[60:63], v[154:157], v[186:189], v[60:63]
	v_mfma_f32_16x16x32_bf16 v[56:59], v[162:165], v[186:189], v[56:59]
	v_mfma_f32_16x16x32_bf16 v[44:47], v[154:157], v[194:197], v[44:47]
	v_mfma_f32_16x16x32_bf16 v[40:43], v[162:165], v[194:197], v[40:43]
	v_mfma_f32_16x16x32_bf16 v[28:31], v[154:157], v[202:205], v[28:31]
	v_mfma_f32_16x16x32_bf16 v[24:27], v[162:165], v[202:205], v[24:27]
	v_mfma_f32_16x16x32_bf16 v[12:15], v[154:157], v[210:213], v[12:15]
	v_mfma_f32_16x16x32_bf16 v[8:11], v[162:165], v[210:213], v[8:11]
	s_setprio 0
	s_setprio 1
	v_mfma_f32_16x16x32_bf16 v[52:55], v[166:169], v[182:185], v[52:55]
	v_mfma_f32_16x16x32_bf16 v[48:51], v[174:177], v[182:185], v[48:51]
	v_mfma_f32_16x16x32_bf16 v[36:39], v[166:169], v[190:193], v[36:39]
	v_mfma_f32_16x16x32_bf16 v[32:35], v[174:177], v[190:193], v[32:35]
	v_mfma_f32_16x16x32_bf16 v[20:23], v[166:169], v[198:201], v[20:23]
	v_mfma_f32_16x16x32_bf16 v[16:19], v[174:177], v[198:201], v[16:19]
	v_mfma_f32_16x16x32_bf16 v[4:7], v[166:169], v[206:209], v[4:7]
	v_mfma_f32_16x16x32_bf16 v[0:3], v[174:177], v[206:209], v[0:3]
	v_mfma_f32_16x16x32_bf16 v[52:55], v[170:173], v[186:189], v[52:55]
	v_mfma_f32_16x16x32_bf16 v[48:51], v[178:181], v[186:189], v[48:51]
	v_mfma_f32_16x16x32_bf16 v[36:39], v[170:173], v[194:197], v[36:39]
	v_mfma_f32_16x16x32_bf16 v[32:35], v[178:181], v[194:197], v[32:35]
	v_mfma_f32_16x16x32_bf16 v[20:23], v[170:173], v[202:205], v[20:23]
	v_mfma_f32_16x16x32_bf16 v[16:19], v[178:181], v[202:205], v[16:19]
	v_mfma_f32_16x16x32_bf16 v[4:7], v[170:173], v[210:213], v[4:7]
	v_mfma_f32_16x16x32_bf16 v[0:3], v[178:181], v[210:213], v[0:3]
	s_setprio 0
	s_barrier
	s_add_i32 s47, s47, 2
	s_add_u32 s20, s20, 0x100
	s_addc_u32 s21, s21, 0
	s_add_u32 s45, s45, 0x100
	s_addc_u32 s46, s46, 0
	s_cmp_gt_u32 s47, 29
	s_cbranch_scc0 .LBB0_1468
	s_branch .Lpeel_after_p6
.LBB0_1468:
	ds_read_b128 v[144:147], v151
	ds_read_b128 v[154:157], v151 offset:1024
	ds_read_b128 v[158:161], v151 offset:2048
	ds_read_b128 v[162:165], v151 offset:3072
	ds_read_b128 v[166:169], v152
	ds_read_b128 v[170:173], v152 offset:1024
	ds_read_b128 v[174:177], v152 offset:2048
	ds_read_b128 v[178:181], v152 offset:3072
	s_add_u32 s22, s20, 0xfff80080
	s_addc_u32 s23, s21, -1
	s_cmp_eq_u32 s47, 28
	s_cselect_b32 s25, s13, s23
	s_cselect_b32 s24, s43, s22
	s_cselect_b32 s23, s11, s46
	s_cselect_b32 s22, s44, s45
	s_add_i32 m0, s19, 0xc000
	ds_read_b128 v[182:185], v153
	ds_read_b128 v[186:189], v153 offset:1024
	ds_read_b128 v[190:193], v153 offset:2048
	ds_read_b128 v[194:197], v153 offset:3072
	ds_read_b128 v[198:201], v153 offset:4096
	ds_read_b128 v[202:205], v153 offset:5120
	ds_read_b128 v[206:209], v153 offset:6144
	ds_read_b128 v[210:213], v153 offset:7168
	global_load_lds_dwordx4 v136, s[20:21]
	s_add_i32 m0, s19, 0xe000
	s_nop 0
	global_load_lds_dwordx4 v138, s[20:21]
	s_waitcnt vmcnt(8)
	s_waitcnt lgkmcnt(0)
	s_barrier
	s_setprio 1
	s_waitcnt lgkmcnt(0)
	v_mfma_f32_16x16x32_bf16 v[124:127], v[144:147], v[182:185], v[124:127]
	v_mfma_f32_16x16x32_bf16 v[120:123], v[158:161], v[182:185], v[120:123]
	v_mfma_f32_16x16x32_bf16 v[108:111], v[144:147], v[190:193], v[108:111]
	v_mfma_f32_16x16x32_bf16 v[104:107], v[158:161], v[190:193], v[104:107]
	v_mfma_f32_16x16x32_bf16 v[92:95], v[144:147], v[198:201], v[92:95]
	v_mfma_f32_16x16x32_bf16 v[88:91], v[158:161], v[198:201], v[88:91]
	v_mfma_f32_16x16x32_bf16 v[76:79], v[144:147], v[206:209], v[76:79]
	v_mfma_f32_16x16x32_bf16 v[72:75], v[158:161], v[206:209], v[72:75]
	v_mfma_f32_16x16x32_bf16 v[124:127], v[154:157], v[186:189], v[124:127]
	v_mfma_f32_16x16x32_bf16 v[120:123], v[162:165], v[186:189], v[120:123]
	v_mfma_f32_16x16x32_bf16 v[108:111], v[154:157], v[194:197], v[108:111]
	v_mfma_f32_16x16x32_bf16 v[104:107], v[162:165], v[194:197], v[104:107]
	v_mfma_f32_16x16x32_bf16 v[92:95], v[154:157], v[202:205], v[92:95]
	v_mfma_f32_16x16x32_bf16 v[88:91], v[162:165], v[202:205], v[88:91]
	v_mfma_f32_16x16x32_bf16 v[76:79], v[154:157], v[210:213], v[76:79]
	v_mfma_f32_16x16x32_bf16 v[72:75], v[162:165], v[210:213], v[72:75]
	s_setprio 0
	s_setprio 1
	v_mfma_f32_16x16x32_bf16 v[116:119], v[166:169], v[182:185], v[116:119]
	v_mfma_f32_16x16x32_bf16 v[112:115], v[174:177], v[182:185], v[112:115]
	v_mfma_f32_16x16x32_bf16 v[100:103], v[166:169], v[190:193], v[100:103]
	v_mfma_f32_16x16x32_bf16 v[96:99], v[174:177], v[190:193], v[96:99]
	v_mfma_f32_16x16x32_bf16 v[84:87], v[166:169], v[198:201], v[84:87]
	v_mfma_f32_16x16x32_bf16 v[80:83], v[174:177], v[198:201], v[80:83]
	v_mfma_f32_16x16x32_bf16 v[68:71], v[166:169], v[206:209], v[68:71]
	v_mfma_f32_16x16x32_bf16 v[64:67], v[174:177], v[206:209], v[64:67]
	v_mfma_f32_16x16x32_bf16 v[116:119], v[170:173], v[186:189], v[116:119]
	v_mfma_f32_16x16x32_bf16 v[112:115], v[178:181], v[186:189], v[112:115]
	v_mfma_f32_16x16x32_bf16 v[100:103], v[170:173], v[194:197], v[100:103]
	v_mfma_f32_16x16x32_bf16 v[96:99], v[178:181], v[194:197], v[96:99]
	v_mfma_f32_16x16x32_bf16 v[84:87], v[170:173], v[202:205], v[84:87]
	v_mfma_f32_16x16x32_bf16 v[80:83], v[178:181], v[202:205], v[80:83]
	v_mfma_f32_16x16x32_bf16 v[68:71], v[170:173], v[210:213], v[68:71]
	v_mfma_f32_16x16x32_bf16 v[64:67], v[178:181], v[210:213], v[64:67]
	s_setprio 0
	s_barrier
	s_add_i32 s48, s40, s31
	s_add_u32 s70, s22, 0x80
	s_addc_u32 s71, s23, 0
	s_mov_b32 m0, s48
	ds_read_b128 v[182:185], v153 offset:16384
	ds_read_b128 v[186:189], v153 offset:17408
	ds_read_b128 v[190:193], v153 offset:18432
	ds_read_b128 v[194:197], v153 offset:19456
	ds_read_b128 v[198:201], v153 offset:20480
	ds_read_b128 v[202:205], v153 offset:21504
	ds_read_b128 v[206:209], v153 offset:22528
	ds_read_b128 v[210:213], v153 offset:23552
	global_load_lds_dwordx4 v130, s[22:23]
	s_add_i32 m0, s48, 0x2000
	s_add_u32 s48, s22, 0x80000
	s_addc_u32 s49, s23, 0
	s_add_i32 s50, s41, s31
	global_load_lds_dwordx4 v134, s[22:23]
	s_mov_b32 m0, s50
	s_nop 0
	global_load_lds_dwordx4 v130, s[48:49]
	s_add_i32 m0, s50, 0x2000
	s_nop 0
	global_load_lds_dwordx4 v134, s[48:49]
	s_add_u32 s74, s24, 0x80
	s_addc_u32 s75, s25, 0
	s_mov_b32 m0, s19
	s_nop 0
	global_load_lds_dwordx4 v128, s[24:25]
	s_mov_b32 m0, s33
	s_nop 0
	global_load_lds_dwordx4 v132, s[24:25]
	s_waitcnt vmcnt(8)
	s_waitcnt lgkmcnt(0)
	s_barrier
	s_setprio 1
	s_waitcnt lgkmcnt(0)
	v_mfma_f32_16x16x32_bf16 v[60:63], v[144:147], v[182:185], v[60:63]
	v_mfma_f32_16x16x32_bf16 v[56:59], v[158:161], v[182:185], v[56:59]
	v_mfma_f32_16x16x32_bf16 v[44:47], v[144:147], v[190:193], v[44:47]
	v_mfma_f32_16x16x32_bf16 v[40:43], v[158:161], v[190:193], v[40:43]
	v_mfma_f32_16x16x32_bf16 v[28:31], v[144:147], v[198:201], v[28:31]
	v_mfma_f32_16x16x32_bf16 v[24:27], v[158:161], v[198:201], v[24:27]
	v_mfma_f32_16x16x32_bf16 v[12:15], v[144:147], v[206:209], v[12:15]
	v_mfma_f32_16x16x32_bf16 v[8:11], v[158:161], v[206:209], v[8:11]
	v_mfma_f32_16x16x32_bf16 v[60:63], v[154:157], v[186:189], v[60:63]
	v_mfma_f32_16x16x32_bf16 v[56:59], v[162:165], v[186:189], v[56:59]
	v_mfma_f32_16x16x32_bf16 v[44:47], v[154:157], v[194:197], v[44:47]
	v_mfma_f32_16x16x32_bf16 v[40:43], v[162:165], v[194:197], v[40:43]
	v_mfma_f32_16x16x32_bf16 v[28:31], v[154:157], v[202:205], v[28:31]
	v_mfma_f32_16x16x32_bf16 v[24:27], v[162:165], v[202:205], v[24:27]
	v_mfma_f32_16x16x32_bf16 v[12:15], v[154:157], v[210:213], v[12:15]
	v_mfma_f32_16x16x32_bf16 v[8:11], v[162:165], v[210:213], v[8:11]
	s_setprio 0
	s_setprio 1
	v_mfma_f32_16x16x32_bf16 v[52:55], v[166:169], v[182:185], v[52:55]
	v_mfma_f32_16x16x32_bf16 v[48:51], v[174:177], v[182:185], v[48:51]
	v_mfma_f32_16x16x32_bf16 v[36:39], v[166:169], v[190:193], v[36:39]
	v_mfma_f32_16x16x32_bf16 v[32:35], v[174:177], v[190:193], v[32:35]
	v_mfma_f32_16x16x32_bf16 v[20:23], v[166:169], v[198:201], v[20:23]
	v_mfma_f32_16x16x32_bf16 v[16:19], v[174:177], v[198:201], v[16:19]
	v_mfma_f32_16x16x32_bf16 v[4:7], v[166:169], v[206:209], v[4:7]
	v_mfma_f32_16x16x32_bf16 v[0:3], v[174:177], v[206:209], v[0:3]
	v_mfma_f32_16x16x32_bf16 v[52:55], v[170:173], v[186:189], v[52:55]
	v_mfma_f32_16x16x32_bf16 v[48:51], v[178:181], v[186:189], v[48:51]
	v_mfma_f32_16x16x32_bf16 v[36:39], v[170:173], v[194:197], v[36:39]
	v_mfma_f32_16x16x32_bf16 v[32:35], v[178:181], v[194:197], v[32:35]
	v_mfma_f32_16x16x32_bf16 v[20:23], v[170:173], v[202:205], v[20:23]
	v_mfma_f32_16x16x32_bf16 v[16:19], v[178:181], v[202:205], v[16:19]
	v_mfma_f32_16x16x32_bf16 v[4:7], v[170:173], v[210:213], v[4:7]
	v_mfma_f32_16x16x32_bf16 v[0:3], v[178:181], v[210:213], v[0:3]
	s_setprio 0
	s_barrier
	s_add_i32 s48, 0, 0x18000
	s_add_i32 s49, 0, 0x1c000
	v_add_u32_e32 v162, s48, v149
	v_add_u32_e32 v178, s49, v149
	ds_read_b128 v[144:147], v162
	ds_read_b128 v[154:157], v162 offset:1024
	ds_read_b128 v[158:161], v162 offset:2048
	ds_read_b128 v[162:165], v162 offset:3072
	ds_read_b128 v[166:169], v178
	ds_read_b128 v[170:173], v178 offset:1024
	ds_read_b128 v[174:177], v178 offset:2048
	ds_read_b128 v[178:181], v178 offset:3072
	s_add_u32 s24, s24, 0x80000
	s_addc_u32 s25, s25, 0
	s_mov_b32 m0, s34
	ds_read_b128 v[182:185], v153 offset:32768
	ds_read_b128 v[186:189], v153 offset:33792
	ds_read_b128 v[190:193], v153 offset:34816
	ds_read_b128 v[194:197], v153 offset:35840
	ds_read_b128 v[198:201], v153 offset:36864
	ds_read_b128 v[202:205], v153 offset:37888
	ds_read_b128 v[206:209], v153 offset:38912
	ds_read_b128 v[210:213], v153 offset:39936
	global_load_lds_dwordx4 v128, s[24:25]
	s_mov_b32 m0, s35
	s_nop 0
	global_load_lds_dwordx4 v132, s[24:25]
	s_waitcnt vmcnt(8)
	s_waitcnt lgkmcnt(0)
	s_barrier
	s_setprio 1
	s_waitcnt lgkmcnt(0)
	v_mfma_f32_16x16x32_bf16 v[124:127], v[144:147], v[182:185], v[124:127]
	v_mfma_f32_16x16x32_bf16 v[120:123], v[158:161], v[182:185], v[120:123]
	v_mfma_f32_16x16x32_bf16 v[108:111], v[144:147], v[190:193], v[108:111]
	v_mfma_f32_16x16x32_bf16 v[104:107], v[158:161], v[190:193], v[104:107]
	v_mfma_f32_16x16x32_bf16 v[92:95], v[144:147], v[198:201], v[92:95]
	v_mfma_f32_16x16x32_bf16 v[88:91], v[158:161], v[198:201], v[88:91]
	v_mfma_f32_16x16x32_bf16 v[76:79], v[144:147], v[206:209], v[76:79]
	v_mfma_f32_16x16x32_bf16 v[72:75], v[158:161], v[206:209], v[72:75]
	v_mfma_f32_16x16x32_bf16 v[124:127], v[154:157], v[186:189], v[124:127]
	v_mfma_f32_16x16x32_bf16 v[120:123], v[162:165], v[186:189], v[120:123]
	v_mfma_f32_16x16x32_bf16 v[108:111], v[154:157], v[194:197], v[108:111]
	v_mfma_f32_16x16x32_bf16 v[104:107], v[162:165], v[194:197], v[104:107]
	v_mfma_f32_16x16x32_bf16 v[92:95], v[154:157], v[202:205], v[92:95]
	v_mfma_f32_16x16x32_bf16 v[88:91], v[162:165], v[202:205], v[88:91]
	v_mfma_f32_16x16x32_bf16 v[76:79], v[154:157], v[210:213], v[76:79]
	v_mfma_f32_16x16x32_bf16 v[72:75], v[162:165], v[210:213], v[72:75]
	s_setprio 0
	s_setprio 1
	v_mfma_f32_16x16x32_bf16 v[116:119], v[166:169], v[182:185], v[116:119]
	v_mfma_f32_16x16x32_bf16 v[112:115], v[174:177], v[182:185], v[112:115]
	v_mfma_f32_16x16x32_bf16 v[100:103], v[166:169], v[190:193], v[100:103]
	v_mfma_f32_16x16x32_bf16 v[96:99], v[174:177], v[190:193], v[96:99]
	v_mfma_f32_16x16x32_bf16 v[84:87], v[166:169], v[198:201], v[84:87]
	v_mfma_f32_16x16x32_bf16 v[80:83], v[174:177], v[198:201], v[80:83]
	v_mfma_f32_16x16x32_bf16 v[68:71], v[166:169], v[206:209], v[68:71]
	v_mfma_f32_16x16x32_bf16 v[64:67], v[174:177], v[206:209], v[64:67]
	v_mfma_f32_16x16x32_bf16 v[116:119], v[170:173], v[186:189], v[116:119]
	v_mfma_f32_16x16x32_bf16 v[112:115], v[178:181], v[186:189], v[112:115]
	v_mfma_f32_16x16x32_bf16 v[100:103], v[170:173], v[194:197], v[100:103]
	v_mfma_f32_16x16x32_bf16 v[96:99], v[178:181], v[194:197], v[96:99]
	v_mfma_f32_16x16x32_bf16 v[84:87], v[170:173], v[202:205], v[84:87]
	v_mfma_f32_16x16x32_bf16 v[80:83], v[178:181], v[202:205], v[80:83]
	v_mfma_f32_16x16x32_bf16 v[68:71], v[170:173], v[210:213], v[68:71]
	v_mfma_f32_16x16x32_bf16 v[64:67], v[178:181], v[210:213], v[64:67]
	s_setprio 0
	s_barrier
	s_add_i32 s24, s48, s31
	s_mov_b32 m0, s24
	ds_read_b128 v[182:185], v153 offset:49152
	ds_read_b128 v[186:189], v153 offset:50176
	ds_read_b128 v[190:193], v153 offset:51200
	ds_read_b128 v[194:197], v153 offset:52224
	ds_read_b128 v[198:201], v153 offset:53248
	ds_read_b128 v[202:205], v153 offset:54272
	ds_read_b128 v[206:209], v153 offset:55296
	ds_read_b128 v[210:213], v153 offset:56320
	global_load_lds_dwordx4 v130, s[70:71]
	s_add_i32 m0, s24, 0x2000
	s_add_u32 s22, s22, 0x80080
	s_addc_u32 s23, s23, 0
	s_add_i32 s24, s49, s31
	global_load_lds_dwordx4 v134, s[70:71]
	s_mov_b32 m0, s24
	s_nop 0
	global_load_lds_dwordx4 v130, s[22:23]
	s_add_i32 m0, s24, 0x2000
	s_nop 0
	global_load_lds_dwordx4 v134, s[22:23]
	s_mov_b32 m0, s37
	s_nop 0
	global_load_lds_dwordx4 v128, s[74:75]
	s_mov_b32 m0, s38
	s_nop 0
	global_load_lds_dwordx4 v132, s[74:75]
	s_waitcnt vmcnt(8)
	s_waitcnt lgkmcnt(0)
	s_barrier
	s_setprio 1
	s_waitcnt lgkmcnt(0)
	v_mfma_f32_16x16x32_bf16 v[60:63], v[144:147], v[182:185], v[60:63]
	v_mfma_f32_16x16x32_bf16 v[56:59], v[158:161], v[182:185], v[56:59]
	v_mfma_f32_16x16x32_bf16 v[44:47], v[144:147], v[190:193], v[44:47]
	v_mfma_f32_16x16x32_bf16 v[40:43], v[158:161], v[190:193], v[40:43]
	v_mfma_f32_16x16x32_bf16 v[28:31], v[144:147], v[198:201], v[28:31]
	v_mfma_f32_16x16x32_bf16 v[24:27], v[158:161], v[198:201], v[24:27]
	v_mfma_f32_16x16x32_bf16 v[12:15], v[144:147], v[206:209], v[12:15]
	v_mfma_f32_16x16x32_bf16 v[8:11], v[158:161], v[206:209], v[8:11]
	v_mfma_f32_16x16x32_bf16 v[60:63], v[154:157], v[186:189], v[60:63]
	v_mfma_f32_16x16x32_bf16 v[56:59], v[162:165], v[186:189], v[56:59]
	v_mfma_f32_16x16x32_bf16 v[44:47], v[154:157], v[194:197], v[44:47]
	v_mfma_f32_16x16x32_bf16 v[40:43], v[162:165], v[194:197], v[40:43]
	v_mfma_f32_16x16x32_bf16 v[28:31], v[154:157], v[202:205], v[28:31]
	v_mfma_f32_16x16x32_bf16 v[24:27], v[162:165], v[202:205], v[24:27]
	v_mfma_f32_16x16x32_bf16 v[12:15], v[154:157], v[210:213], v[12:15]
	v_mfma_f32_16x16x32_bf16 v[8:11], v[162:165], v[210:213], v[8:11]
	s_setprio 0
	s_setprio 1
	v_mfma_f32_16x16x32_bf16 v[52:55], v[166:169], v[182:185], v[52:55]
	v_mfma_f32_16x16x32_bf16 v[48:51], v[174:177], v[182:185], v[48:51]
	v_mfma_f32_16x16x32_bf16 v[36:39], v[166:169], v[190:193], v[36:39]
	v_mfma_f32_16x16x32_bf16 v[32:35], v[174:177], v[190:193], v[32:35]
	v_mfma_f32_16x16x32_bf16 v[20:23], v[166:169], v[198:201], v[20:23]
	v_mfma_f32_16x16x32_bf16 v[16:19], v[174:177], v[198:201], v[16:19]
	v_mfma_f32_16x16x32_bf16 v[4:7], v[166:169], v[206:209], v[4:7]
	v_mfma_f32_16x16x32_bf16 v[0:3], v[174:177], v[206:209], v[0:3]
	v_mfma_f32_16x16x32_bf16 v[52:55], v[170:173], v[186:189], v[52:55]
	v_mfma_f32_16x16x32_bf16 v[48:51], v[178:181], v[186:189], v[48:51]
	v_mfma_f32_16x16x32_bf16 v[36:39], v[170:173], v[194:197], v[36:39]
	v_mfma_f32_16x16x32_bf16 v[32:35], v[178:181], v[194:197], v[32:35]
	v_mfma_f32_16x16x32_bf16 v[20:23], v[170:173], v[202:205], v[20:23]
	v_mfma_f32_16x16x32_bf16 v[16:19], v[178:181], v[202:205], v[16:19]
	v_mfma_f32_16x16x32_bf16 v[4:7], v[170:173], v[210:213], v[4:7]
	v_mfma_f32_16x16x32_bf16 v[0:3], v[178:181], v[210:213], v[0:3]
	s_setprio 0
	s_barrier
	s_add_i32 s47, s47, 2
	s_add_u32 s20, s20, 0x100
	s_addc_u32 s21, s21, 0
	s_add_u32 s45, s45, 0x100
	s_addc_u32 s46, s46, 0
	s_cmp_gt_u32 s47, 29
	s_cbranch_scc0 .LBB0_1468
